# k20 + lever 9: GEMM main loops' per-iteration scalar set-up moved in front of the loop-back barrier (5 loops)
# baseline (speedup 1.0000x reference)
.LBB0_325:
	s_ashr_i32 s9, s8, 31
	s_lshl_b64 s[10:11], s[8:9], 19
	v_readlane_b32 s12, v254, 43
	v_readlane_b32 s13, v254, 44
	s_add_u32 s10, s12, s10
	s_addc_u32 s11, s13, s11
	s_and_b64 s[12:13], s[6:7], exec
	s_cselect_b32 s9, s11, s17
	s_cselect_b32 s36, s10, s16
	s_ashr_i32 s3, s2, 31
	s_lshl_b64 s[12:13], s[2:3], 19
	s_add_u32 s12, s22, s12
	s_addc_u32 s13, s23, s13
	s_and_b64 s[20:21], s[6:7], exec
	s_cselect_b32 s3, s13, s19
	s_cselect_b32 s40, s12, s18
	s_add_u32 s16, s16, 0x40080
	s_addc_u32 s17, s17, 0
	s_add_u32 s41, s18, 0x100
	v_mov_b32_e32 v2, 0
	s_addc_u32 s42, s19, 0
	s_mov_b32 s43, -2
	v_mov_b32_e32 v3, v2
	v_mov_b32_e32 v4, v2
	v_mov_b32_e32 v5, v2
	v_mov_b32_e32 v10, v2
	v_mov_b32_e32 v11, v2
	v_mov_b32_e32 v12, v2
	v_mov_b32_e32 v13, v2
	v_mov_b32_e32 v18, v2
	v_mov_b32_e32 v19, v2
	v_mov_b32_e32 v20, v2
	v_mov_b32_e32 v21, v2
	v_mov_b32_e32 v26, v2
	v_mov_b32_e32 v27, v2
	v_mov_b32_e32 v28, v2
	v_mov_b32_e32 v29, v2
	v_mov_b32_e32 v34, v2
	v_mov_b32_e32 v35, v2
	v_mov_b32_e32 v36, v2
	v_mov_b32_e32 v37, v2
	v_mov_b32_e32 v42, v2
	v_mov_b32_e32 v43, v2
	v_mov_b32_e32 v44, v2
	v_mov_b32_e32 v45, v2
	v_mov_b32_e32 v50, v2
	v_mov_b32_e32 v51, v2
	v_mov_b32_e32 v52, v2
	v_mov_b32_e32 v53, v2
	v_mov_b32_e32 v58, v2
	v_mov_b32_e32 v59, v2
	v_mov_b32_e32 v60, v2
	v_mov_b32_e32 v61, v2
	v_mov_b32_e32 v6, v2
	v_mov_b32_e32 v7, v2
	v_mov_b32_e32 v8, v2
	v_mov_b32_e32 v9, v2
	v_mov_b32_e32 v14, v2
	v_mov_b32_e32 v15, v2
	v_mov_b32_e32 v16, v2
	v_mov_b32_e32 v17, v2
	v_mov_b32_e32 v22, v2
	v_mov_b32_e32 v23, v2
	v_mov_b32_e32 v24, v2
	v_mov_b32_e32 v25, v2
	v_mov_b32_e32 v30, v2
	v_mov_b32_e32 v31, v2
	v_mov_b32_e32 v32, v2
	v_mov_b32_e32 v33, v2
	v_mov_b32_e32 v38, v2
	v_mov_b32_e32 v39, v2
	v_mov_b32_e32 v40, v2
	v_mov_b32_e32 v41, v2
	v_mov_b32_e32 v46, v2
	v_mov_b32_e32 v47, v2
	v_mov_b32_e32 v48, v2
	v_mov_b32_e32 v49, v2
	v_mov_b32_e32 v54, v2
	v_mov_b32_e32 v55, v2
	v_mov_b32_e32 v56, v2
	v_mov_b32_e32 v57, v2
	v_mov_b32_e32 v62, v2
	v_mov_b32_e32 v63, v2
	v_mov_b32_e32 v64, v2
	v_mov_b32_e32 v65, v2
	v_mov_b32_e32 v66, v2
	v_mov_b32_e32 v67, v2
	v_mov_b32_e32 v68, v2
	v_mov_b32_e32 v69, v2
	v_mov_b32_e32 v74, v2
	v_mov_b32_e32 v75, v2
	v_mov_b32_e32 v76, v2
	v_mov_b32_e32 v77, v2
	v_mov_b32_e32 v82, v2
	v_mov_b32_e32 v83, v2
	v_mov_b32_e32 v84, v2
	v_mov_b32_e32 v85, v2
	v_mov_b32_e32 v90, v2
	v_mov_b32_e32 v91, v2
	v_mov_b32_e32 v92, v2
	v_mov_b32_e32 v93, v2
	v_mov_b32_e32 v98, v2
	v_mov_b32_e32 v99, v2
	v_mov_b32_e32 v100, v2
	v_mov_b32_e32 v101, v2
	v_mov_b32_e32 v106, v2
	v_mov_b32_e32 v107, v2
	v_mov_b32_e32 v108, v2
	v_mov_b32_e32 v109, v2
	v_mov_b32_e32 v114, v2
	v_mov_b32_e32 v115, v2
	v_mov_b32_e32 v116, v2
	v_mov_b32_e32 v117, v2
	v_mov_b32_e32 v122, v2
	v_mov_b32_e32 v123, v2
	v_mov_b32_e32 v124, v2
	v_mov_b32_e32 v125, v2
	v_mov_b32_e32 v70, v2
	v_mov_b32_e32 v71, v2
	v_mov_b32_e32 v72, v2
	v_mov_b32_e32 v73, v2
	v_mov_b32_e32 v78, v2
	v_mov_b32_e32 v79, v2
	v_mov_b32_e32 v80, v2
	v_mov_b32_e32 v81, v2
	v_mov_b32_e32 v86, v2
	v_mov_b32_e32 v87, v2
	v_mov_b32_e32 v88, v2
	v_mov_b32_e32 v89, v2
	v_mov_b32_e32 v94, v2
	v_mov_b32_e32 v95, v2
	v_mov_b32_e32 v96, v2
	v_mov_b32_e32 v97, v2
	v_mov_b32_e32 v102, v2
	v_mov_b32_e32 v103, v2
	v_mov_b32_e32 v104, v2
	v_mov_b32_e32 v105, v2
	v_mov_b32_e32 v110, v2
	v_mov_b32_e32 v111, v2
	v_mov_b32_e32 v112, v2
	v_mov_b32_e32 v113, v2
	v_mov_b32_e32 v118, v2
	v_mov_b32_e32 v119, v2
	v_mov_b32_e32 v120, v2
	v_mov_b32_e32 v121, v2
	v_mov_b32_e32 v126, v2
	v_mov_b32_e32 v127, v2
	v_mov_b32_e32 v128, v2
	v_mov_b32_e32 v129, v2
	s_mov_b64 s[48:49], 0x80
	s_add_u32 s18, s16, 0xfffc0080
	s_addc_u32 s19, s17, -1
	s_add_i32 s44, 0, 0x10000
	s_cmp_eq_u32 s43, 12
	s_cselect_b32 s21, s9, s19
	s_cselect_b32 s20, s36, s18
	s_cselect_b32 s19, s3, s42
	s_cselect_b32 s18, s40, s41
	s_add_i32 s46, 0, 0x14000
.LBB0_326:
	v_add_u32_e32 v156, s44, v146
	v_add_u32_e32 v172, s46, v146
	ds_read_b128 v[140:143], v156
	ds_read_b128 v[148:151], v156 offset:1024
	ds_read_b128 v[152:155], v156 offset:2048
	ds_read_b128 v[156:159], v156 offset:3072
	ds_read_b128 v[160:163], v172
	ds_read_b128 v[164:167], v172 offset:1024
	ds_read_b128 v[168:171], v172 offset:2048
	ds_read_b128 v[172:175], v172 offset:3072
	v_lshl_add_u64 v[196:197], s[16:17], 0, v[136:137]
	s_add_i32 m0, s26, 0xc000
	ds_read_b128 v[176:179], v147
	ds_read_b128 v[180:183], v147 offset:1024
	ds_read_b128 v[184:187], v147 offset:2048
	ds_read_b128 v[188:191], v147 offset:3072
	ds_read_b128 v[192:195], v147 offset:4096
	ds_read_b128 v[206:209], v147 offset:5120
	ds_read_b128 v[210:213], v147 offset:6144
	ds_read_b128 v[214:217], v147 offset:7168
	global_load_lds_dwordx4 v[196:197], off
	v_lshl_add_u64 v[196:197], s[16:17], 0, v[138:139]
	s_add_i32 m0, s26, 0xe000
	s_nop 0
	global_load_lds_dwordx4 v[196:197], off
	s_waitcnt vmcnt(8)
	s_waitcnt lgkmcnt(0)
	s_barrier
	s_setprio 1
	s_waitcnt lgkmcnt(0)
	v_mfma_f32_16x16x32_bf16 v[126:129], v[140:143], v[176:179], v[126:129]
	v_mfma_f32_16x16x32_bf16 v[118:121], v[152:155], v[176:179], v[118:121]
	v_mfma_f32_16x16x32_bf16 v[110:113], v[140:143], v[184:187], v[110:113]
	v_mfma_f32_16x16x32_bf16 v[102:105], v[152:155], v[184:187], v[102:105]
	v_mfma_f32_16x16x32_bf16 v[94:97], v[140:143], v[192:195], v[94:97]
	v_mfma_f32_16x16x32_bf16 v[86:89], v[152:155], v[192:195], v[86:89]
	v_mfma_f32_16x16x32_bf16 v[78:81], v[140:143], v[210:213], v[78:81]
	v_mfma_f32_16x16x32_bf16 v[70:73], v[152:155], v[210:213], v[70:73]
	v_mfma_f32_16x16x32_bf16 v[126:129], v[148:151], v[180:183], v[126:129]
	v_mfma_f32_16x16x32_bf16 v[118:121], v[156:159], v[180:183], v[118:121]
	v_mfma_f32_16x16x32_bf16 v[110:113], v[148:151], v[188:191], v[110:113]
	v_mfma_f32_16x16x32_bf16 v[102:105], v[156:159], v[188:191], v[102:105]
	v_mfma_f32_16x16x32_bf16 v[94:97], v[148:151], v[206:209], v[94:97]
	v_mfma_f32_16x16x32_bf16 v[86:89], v[156:159], v[206:209], v[86:89]
	v_mfma_f32_16x16x32_bf16 v[78:81], v[148:151], v[214:217], v[78:81]
	v_mfma_f32_16x16x32_bf16 v[70:73], v[156:159], v[214:217], v[70:73]
	s_setprio 0
	s_setprio 1
	v_mfma_f32_16x16x32_bf16 v[122:125], v[160:163], v[176:179], v[122:125]
	v_mfma_f32_16x16x32_bf16 v[114:117], v[168:171], v[176:179], v[114:117]
	v_mfma_f32_16x16x32_bf16 v[106:109], v[160:163], v[184:187], v[106:109]
	v_mfma_f32_16x16x32_bf16 v[98:101], v[168:171], v[184:187], v[98:101]
	v_mfma_f32_16x16x32_bf16 v[90:93], v[160:163], v[192:195], v[90:93]
	v_mfma_f32_16x16x32_bf16 v[82:85], v[168:171], v[192:195], v[82:85]
	v_mfma_f32_16x16x32_bf16 v[74:77], v[160:163], v[210:213], v[74:77]
	v_mfma_f32_16x16x32_bf16 v[66:69], v[168:171], v[210:213], v[66:69]
	v_mfma_f32_16x16x32_bf16 v[122:125], v[164:167], v[180:183], v[122:125]
	v_mfma_f32_16x16x32_bf16 v[114:117], v[172:175], v[180:183], v[114:117]
	v_mfma_f32_16x16x32_bf16 v[106:109], v[164:167], v[188:191], v[106:109]
	v_mfma_f32_16x16x32_bf16 v[98:101], v[172:175], v[188:191], v[98:101]
	v_mfma_f32_16x16x32_bf16 v[90:93], v[164:167], v[206:209], v[90:93]
	v_mfma_f32_16x16x32_bf16 v[82:85], v[172:175], v[206:209], v[82:85]
	v_mfma_f32_16x16x32_bf16 v[74:77], v[164:167], v[214:217], v[74:77]
	v_mfma_f32_16x16x32_bf16 v[66:69], v[172:175], v[214:217], v[66:69]
	s_setprio 0
	s_barrier
	s_add_i32 s44, s44, s63
	v_lshl_add_u64 v[196:197], s[18:19], 0, v[0:1]
	s_mov_b32 m0, s44
	ds_read_b128 v[176:179], v147 offset:16384
	ds_read_b128 v[180:183], v147 offset:17408
	ds_read_b128 v[184:187], v147 offset:18432
	ds_read_b128 v[188:191], v147 offset:19456
	ds_read_b128 v[192:195], v147 offset:20480
	ds_read_b128 v[206:209], v147 offset:21504
	ds_read_b128 v[210:213], v147 offset:22528
	ds_read_b128 v[214:217], v147 offset:23552
	global_load_lds_dwordx4 v[196:197], off
	s_add_i32 m0, s44, 0x2000
	s_add_u32 s44, s18, 0x40000
	v_lshl_add_u64 v[218:219], s[18:19], 0, v[130:131]
	s_addc_u32 s45, s19, 0
	s_add_i32 s46, s46, s63
	global_load_lds_dwordx4 v[218:219], off
	v_lshl_add_u64 v[220:221], s[44:45], 0, v[0:1]
	s_mov_b32 m0, s46
	v_lshl_add_u64 v[222:223], s[20:21], 0, v[132:133]
	global_load_lds_dwordx4 v[220:221], off
	v_lshl_add_u64 v[220:221], s[44:45], 0, v[130:131]
	s_add_i32 m0, s46, 0x2000
	s_nop 0
	global_load_lds_dwordx4 v[220:221], off
	v_lshl_add_u64 v[220:221], s[20:21], 0, v[134:135]
	s_mov_b32 m0, s26
	s_nop 0
	global_load_lds_dwordx4 v[220:221], off
	s_mov_b32 m0, s27
	s_nop 0
	global_load_lds_dwordx4 v[222:223], off
	s_waitcnt vmcnt(8)
	s_waitcnt lgkmcnt(0)
	s_barrier
	s_setprio 1
	s_waitcnt lgkmcnt(0)
	v_mfma_f32_16x16x32_bf16 v[62:65], v[140:143], v[176:179], v[62:65]
	v_mfma_f32_16x16x32_bf16 v[54:57], v[152:155], v[176:179], v[54:57]
	v_mfma_f32_16x16x32_bf16 v[46:49], v[140:143], v[184:187], v[46:49]
	v_mfma_f32_16x16x32_bf16 v[38:41], v[152:155], v[184:187], v[38:41]
	v_mfma_f32_16x16x32_bf16 v[30:33], v[140:143], v[192:195], v[30:33]
	v_mfma_f32_16x16x32_bf16 v[22:25], v[152:155], v[192:195], v[22:25]
	v_mfma_f32_16x16x32_bf16 v[14:17], v[140:143], v[210:213], v[14:17]
	v_mfma_f32_16x16x32_bf16 v[6:9], v[152:155], v[210:213], v[6:9]
	v_mfma_f32_16x16x32_bf16 v[62:65], v[148:151], v[180:183], v[62:65]
	v_mfma_f32_16x16x32_bf16 v[54:57], v[156:159], v[180:183], v[54:57]
	v_mfma_f32_16x16x32_bf16 v[46:49], v[148:151], v[188:191], v[46:49]
	v_mfma_f32_16x16x32_bf16 v[38:41], v[156:159], v[188:191], v[38:41]
	v_mfma_f32_16x16x32_bf16 v[30:33], v[148:151], v[206:209], v[30:33]
	v_mfma_f32_16x16x32_bf16 v[22:25], v[156:159], v[206:209], v[22:25]
	v_mfma_f32_16x16x32_bf16 v[14:17], v[148:151], v[214:217], v[14:17]
	v_mfma_f32_16x16x32_bf16 v[6:9], v[156:159], v[214:217], v[6:9]
	s_setprio 0
	s_setprio 1
	v_mfma_f32_16x16x32_bf16 v[58:61], v[160:163], v[176:179], v[58:61]
	v_mfma_f32_16x16x32_bf16 v[50:53], v[168:171], v[176:179], v[50:53]
	v_mfma_f32_16x16x32_bf16 v[42:45], v[160:163], v[184:187], v[42:45]
	v_mfma_f32_16x16x32_bf16 v[34:37], v[168:171], v[184:187], v[34:37]
	v_mfma_f32_16x16x32_bf16 v[26:29], v[160:163], v[192:195], v[26:29]
	v_mfma_f32_16x16x32_bf16 v[18:21], v[168:171], v[192:195], v[18:21]
	v_mfma_f32_16x16x32_bf16 v[10:13], v[160:163], v[210:213], v[10:13]
	v_mfma_f32_16x16x32_bf16 v[2:5], v[168:171], v[210:213], v[2:5]
	v_mfma_f32_16x16x32_bf16 v[58:61], v[164:167], v[180:183], v[58:61]
	v_mfma_f32_16x16x32_bf16 v[50:53], v[172:175], v[180:183], v[50:53]
	v_mfma_f32_16x16x32_bf16 v[42:45], v[164:167], v[188:191], v[42:45]
	v_mfma_f32_16x16x32_bf16 v[34:37], v[172:175], v[188:191], v[34:37]
	v_mfma_f32_16x16x32_bf16 v[26:29], v[164:167], v[206:209], v[26:29]
	v_mfma_f32_16x16x32_bf16 v[18:21], v[172:175], v[206:209], v[18:21]
	v_mfma_f32_16x16x32_bf16 v[10:13], v[164:167], v[214:217], v[10:13]
	v_mfma_f32_16x16x32_bf16 v[2:5], v[172:175], v[214:217], v[2:5]
	s_setprio 0
	s_barrier
	s_add_i32 s44, 0, 0x18000
	s_add_i32 s45, 0, 0x1c000
	v_add_u32_e32 v156, s44, v146
	v_add_u32_e32 v172, s45, v146
	ds_read_b128 v[140:143], v156
	ds_read_b128 v[148:151], v156 offset:1024
	ds_read_b128 v[152:155], v156 offset:2048
	ds_read_b128 v[156:159], v156 offset:3072
	ds_read_b128 v[160:163], v172
	ds_read_b128 v[164:167], v172 offset:1024
	ds_read_b128 v[168:171], v172 offset:2048
	ds_read_b128 v[172:175], v172 offset:3072
	s_add_u32 s20, s20, 0x40000
	s_addc_u32 s21, s21, 0
	s_mov_b32 m0, s28
	v_lshl_add_u64 v[224:225], s[20:21], 0, v[134:135]
	ds_read_b128 v[176:179], v147 offset:32768
	ds_read_b128 v[180:183], v147 offset:33792
	ds_read_b128 v[184:187], v147 offset:34816
	ds_read_b128 v[188:191], v147 offset:35840
	ds_read_b128 v[192:195], v147 offset:36864
	ds_read_b128 v[206:209], v147 offset:37888
	ds_read_b128 v[210:213], v147 offset:38912
	ds_read_b128 v[214:217], v147 offset:39936
	global_load_lds_dwordx4 v[224:225], off
	v_lshl_add_u64 v[224:225], s[20:21], 0, v[132:133]
	s_mov_b32 m0, s29
	s_nop 0
	global_load_lds_dwordx4 v[224:225], off
	s_waitcnt vmcnt(8)
	s_waitcnt lgkmcnt(0)
	s_barrier
	s_setprio 1
	s_waitcnt lgkmcnt(0)
	v_mfma_f32_16x16x32_bf16 v[126:129], v[140:143], v[176:179], v[126:129]
	v_mfma_f32_16x16x32_bf16 v[118:121], v[152:155], v[176:179], v[118:121]
	v_mfma_f32_16x16x32_bf16 v[110:113], v[140:143], v[184:187], v[110:113]
	v_mfma_f32_16x16x32_bf16 v[102:105], v[152:155], v[184:187], v[102:105]
	v_mfma_f32_16x16x32_bf16 v[94:97], v[140:143], v[192:195], v[94:97]
	v_mfma_f32_16x16x32_bf16 v[86:89], v[152:155], v[192:195], v[86:89]
	v_mfma_f32_16x16x32_bf16 v[78:81], v[140:143], v[210:213], v[78:81]
	v_mfma_f32_16x16x32_bf16 v[70:73], v[152:155], v[210:213], v[70:73]
	v_mfma_f32_16x16x32_bf16 v[126:129], v[148:151], v[180:183], v[126:129]
	v_mfma_f32_16x16x32_bf16 v[118:121], v[156:159], v[180:183], v[118:121]
	v_mfma_f32_16x16x32_bf16 v[110:113], v[148:151], v[188:191], v[110:113]
	v_mfma_f32_16x16x32_bf16 v[102:105], v[156:159], v[188:191], v[102:105]
	v_mfma_f32_16x16x32_bf16 v[94:97], v[148:151], v[206:209], v[94:97]
	v_mfma_f32_16x16x32_bf16 v[86:89], v[156:159], v[206:209], v[86:89]
	v_mfma_f32_16x16x32_bf16 v[78:81], v[148:151], v[214:217], v[78:81]
	v_mfma_f32_16x16x32_bf16 v[70:73], v[156:159], v[214:217], v[70:73]
	s_setprio 0
	s_setprio 1
	v_mfma_f32_16x16x32_bf16 v[122:125], v[160:163], v[176:179], v[122:125]
	v_mfma_f32_16x16x32_bf16 v[114:117], v[168:171], v[176:179], v[114:117]
	v_mfma_f32_16x16x32_bf16 v[106:109], v[160:163], v[184:187], v[106:109]
	v_mfma_f32_16x16x32_bf16 v[98:101], v[168:171], v[184:187], v[98:101]
	v_mfma_f32_16x16x32_bf16 v[90:93], v[160:163], v[192:195], v[90:93]
	v_mfma_f32_16x16x32_bf16 v[82:85], v[168:171], v[192:195], v[82:85]
	v_mfma_f32_16x16x32_bf16 v[74:77], v[160:163], v[210:213], v[74:77]
	v_mfma_f32_16x16x32_bf16 v[66:69], v[168:171], v[210:213], v[66:69]
	v_mfma_f32_16x16x32_bf16 v[122:125], v[164:167], v[180:183], v[122:125]
	v_mfma_f32_16x16x32_bf16 v[114:117], v[172:175], v[180:183], v[114:117]
	v_mfma_f32_16x16x32_bf16 v[106:109], v[164:167], v[188:191], v[106:109]
	v_mfma_f32_16x16x32_bf16 v[98:101], v[172:175], v[188:191], v[98:101]
	v_mfma_f32_16x16x32_bf16 v[90:93], v[164:167], v[206:209], v[90:93]
	v_mfma_f32_16x16x32_bf16 v[82:85], v[172:175], v[206:209], v[82:85]
	v_mfma_f32_16x16x32_bf16 v[74:77], v[164:167], v[214:217], v[74:77]
	v_mfma_f32_16x16x32_bf16 v[66:69], v[172:175], v[214:217], v[66:69]
	s_setprio 0
	s_barrier
	s_add_i32 s20, s44, s63
	v_lshl_add_u64 v[196:197], v[196:197], 0, s[48:49]
	s_mov_b32 m0, s20
	ds_read_b128 v[176:179], v147 offset:49152
	ds_read_b128 v[180:183], v147 offset:50176
	ds_read_b128 v[184:187], v147 offset:51200
	ds_read_b128 v[188:191], v147 offset:52224
	ds_read_b128 v[192:195], v147 offset:53248
	ds_read_b128 v[206:209], v147 offset:54272
	ds_read_b128 v[210:213], v147 offset:55296
	ds_read_b128 v[214:217], v147 offset:56320
	global_load_lds_dwordx4 v[196:197], off
	s_add_i32 m0, s20, 0x2000
	s_add_u32 s18, s18, 0x40080
	v_lshl_add_u64 v[196:197], v[218:219], 0, s[48:49]
	s_addc_u32 s19, s19, 0
	s_add_i32 s20, s45, s63
	global_load_lds_dwordx4 v[196:197], off
	v_lshl_add_u64 v[196:197], s[18:19], 0, v[0:1]
	s_mov_b32 m0, s20
	s_nop 0
	global_load_lds_dwordx4 v[196:197], off
	v_lshl_add_u64 v[196:197], s[18:19], 0, v[130:131]
	s_add_i32 m0, s20, 0x2000
	s_nop 0
	global_load_lds_dwordx4 v[196:197], off
	v_lshl_add_u64 v[196:197], v[220:221], 0, s[48:49]
	s_mov_b32 m0, s30
	s_nop 0
	global_load_lds_dwordx4 v[196:197], off
	v_lshl_add_u64 v[196:197], v[222:223], 0, s[48:49]
	s_mov_b32 m0, s34
	s_nop 0
	global_load_lds_dwordx4 v[196:197], off
	s_waitcnt vmcnt(8)
	s_waitcnt lgkmcnt(0)
	s_barrier
	s_setprio 1
	s_waitcnt lgkmcnt(0)
	v_mfma_f32_16x16x32_bf16 v[62:65], v[140:143], v[176:179], v[62:65]
	v_mfma_f32_16x16x32_bf16 v[54:57], v[152:155], v[176:179], v[54:57]
	v_mfma_f32_16x16x32_bf16 v[46:49], v[140:143], v[184:187], v[46:49]
	v_mfma_f32_16x16x32_bf16 v[38:41], v[152:155], v[184:187], v[38:41]
	v_mfma_f32_16x16x32_bf16 v[30:33], v[140:143], v[192:195], v[30:33]
	v_mfma_f32_16x16x32_bf16 v[22:25], v[152:155], v[192:195], v[22:25]
	v_mfma_f32_16x16x32_bf16 v[14:17], v[140:143], v[210:213], v[14:17]
	v_mfma_f32_16x16x32_bf16 v[6:9], v[152:155], v[210:213], v[6:9]
	v_mfma_f32_16x16x32_bf16 v[62:65], v[148:151], v[180:183], v[62:65]
	v_mfma_f32_16x16x32_bf16 v[54:57], v[156:159], v[180:183], v[54:57]
	v_mfma_f32_16x16x32_bf16 v[46:49], v[148:151], v[188:191], v[46:49]
	v_mfma_f32_16x16x32_bf16 v[38:41], v[156:159], v[188:191], v[38:41]
	v_mfma_f32_16x16x32_bf16 v[30:33], v[148:151], v[206:209], v[30:33]
	v_mfma_f32_16x16x32_bf16 v[22:25], v[156:159], v[206:209], v[22:25]
	v_mfma_f32_16x16x32_bf16 v[14:17], v[148:151], v[214:217], v[14:17]
	v_mfma_f32_16x16x32_bf16 v[6:9], v[156:159], v[214:217], v[6:9]
	s_setprio 0
	s_setprio 1
	v_mfma_f32_16x16x32_bf16 v[58:61], v[160:163], v[176:179], v[58:61]
	v_mfma_f32_16x16x32_bf16 v[50:53], v[168:171], v[176:179], v[50:53]
	v_mfma_f32_16x16x32_bf16 v[42:45], v[160:163], v[184:187], v[42:45]
	v_mfma_f32_16x16x32_bf16 v[34:37], v[168:171], v[184:187], v[34:37]
	v_mfma_f32_16x16x32_bf16 v[26:29], v[160:163], v[192:195], v[26:29]
	v_mfma_f32_16x16x32_bf16 v[18:21], v[168:171], v[192:195], v[18:21]
	v_mfma_f32_16x16x32_bf16 v[10:13], v[160:163], v[210:213], v[10:13]
	v_mfma_f32_16x16x32_bf16 v[2:5], v[168:171], v[210:213], v[2:5]
	v_mfma_f32_16x16x32_bf16 v[58:61], v[164:167], v[180:183], v[58:61]
	v_mfma_f32_16x16x32_bf16 v[50:53], v[172:175], v[180:183], v[50:53]
	v_mfma_f32_16x16x32_bf16 v[42:45], v[164:167], v[188:191], v[42:45]
	v_mfma_f32_16x16x32_bf16 v[34:37], v[172:175], v[188:191], v[34:37]
	v_mfma_f32_16x16x32_bf16 v[26:29], v[164:167], v[206:209], v[26:29]
	v_mfma_f32_16x16x32_bf16 v[18:21], v[172:175], v[206:209], v[18:21]
	v_mfma_f32_16x16x32_bf16 v[10:13], v[164:167], v[214:217], v[10:13]
	v_mfma_f32_16x16x32_bf16 v[2:5], v[172:175], v[214:217], v[2:5]
	s_setprio 0
	s_add_i32 s43, s43, 2
	s_add_u32 s16, s16, 0x100
	s_addc_u32 s17, s17, 0
	s_add_u32 s41, s41, 0x100
	s_addc_u32 s42, s42, 0
	s_add_u32 s18, s16, 0xfffc0080
	s_addc_u32 s19, s17, -1
	s_add_i32 s44, 0, 0x10000
	s_cmp_eq_u32 s43, 12
	s_cselect_b32 s21, s9, s19
	s_cselect_b32 s20, s36, s18
	s_cselect_b32 s19, s3, s42
	s_cselect_b32 s18, s40, s41
	s_add_i32 s46, 0, 0x14000
	s_cmp_gt_u32 s43, 13
	s_barrier
	s_cbranch_scc0 .LBB0_326
	v_readlane_b32 s16, v253, 25
	v_readlane_b32 s17, v253, 26
	s_and_b64 vcc, exec, s[16:17]
	s_cbranch_vccz .LBB0_329
	s_barrier

.LBB0_405:
	s_add_u32 s36, s12, 0x100
	v_mov_b32_e32 v2, 0
	s_addc_u32 s41, s13, 0
	s_mov_b32 s42, -2
	v_mov_b32_e32 v3, v2
	v_mov_b32_e32 v4, v2
	v_mov_b32_e32 v5, v2
	v_mov_b32_e32 v34, v2
	v_mov_b32_e32 v35, v2
	v_mov_b32_e32 v36, v2
	v_mov_b32_e32 v37, v2
	v_mov_b32_e32 v6, v2
	v_mov_b32_e32 v7, v2
	v_mov_b32_e32 v8, v2
	v_mov_b32_e32 v9, v2
	v_mov_b32_e32 v38, v2
	v_mov_b32_e32 v39, v2
	v_mov_b32_e32 v40, v2
	v_mov_b32_e32 v41, v2
	v_mov_b32_e32 v10, v2
	v_mov_b32_e32 v11, v2
	v_mov_b32_e32 v12, v2
	v_mov_b32_e32 v13, v2
	v_mov_b32_e32 v42, v2
	v_mov_b32_e32 v43, v2
	v_mov_b32_e32 v44, v2
	v_mov_b32_e32 v45, v2
	v_mov_b32_e32 v14, v2
	v_mov_b32_e32 v15, v2
	v_mov_b32_e32 v16, v2
	v_mov_b32_e32 v17, v2
	v_mov_b32_e32 v46, v2
	v_mov_b32_e32 v47, v2
	v_mov_b32_e32 v48, v2
	v_mov_b32_e32 v49, v2
	v_mov_b32_e32 v66, v2
	v_mov_b32_e32 v67, v2
	v_mov_b32_e32 v68, v2
	v_mov_b32_e32 v69, v2
	v_mov_b32_e32 v98, v2
	v_mov_b32_e32 v99, v2
	v_mov_b32_e32 v100, v2
	v_mov_b32_e32 v101, v2
	v_mov_b32_e32 v70, v2
	v_mov_b32_e32 v71, v2
	v_mov_b32_e32 v72, v2
	v_mov_b32_e32 v73, v2
	v_mov_b32_e32 v102, v2
	v_mov_b32_e32 v103, v2
	v_mov_b32_e32 v104, v2
	v_mov_b32_e32 v105, v2
	v_mov_b32_e32 v74, v2
	v_mov_b32_e32 v75, v2
	v_mov_b32_e32 v76, v2
	v_mov_b32_e32 v77, v2
	v_mov_b32_e32 v106, v2
	v_mov_b32_e32 v107, v2
	v_mov_b32_e32 v108, v2
	v_mov_b32_e32 v109, v2
	v_mov_b32_e32 v78, v2
	v_mov_b32_e32 v79, v2
	v_mov_b32_e32 v80, v2
	v_mov_b32_e32 v81, v2
	v_mov_b32_e32 v110, v2
	v_mov_b32_e32 v111, v2
	v_mov_b32_e32 v112, v2
	v_mov_b32_e32 v113, v2
	v_mov_b32_e32 v18, v2
	v_mov_b32_e32 v19, v2
	v_mov_b32_e32 v20, v2
	v_mov_b32_e32 v21, v2
	v_mov_b32_e32 v50, v2
	v_mov_b32_e32 v51, v2
	v_mov_b32_e32 v52, v2
	v_mov_b32_e32 v53, v2
	v_mov_b32_e32 v22, v2
	v_mov_b32_e32 v23, v2
	v_mov_b32_e32 v24, v2
	v_mov_b32_e32 v25, v2
	v_mov_b32_e32 v54, v2
	v_mov_b32_e32 v55, v2
	v_mov_b32_e32 v56, v2
	v_mov_b32_e32 v57, v2
	v_mov_b32_e32 v26, v2
	v_mov_b32_e32 v27, v2
	v_mov_b32_e32 v28, v2
	v_mov_b32_e32 v29, v2
	v_mov_b32_e32 v58, v2
	v_mov_b32_e32 v59, v2
	v_mov_b32_e32 v60, v2
	v_mov_b32_e32 v61, v2
	v_mov_b32_e32 v30, v2
	v_mov_b32_e32 v31, v2
	v_mov_b32_e32 v32, v2
	v_mov_b32_e32 v33, v2
	v_mov_b32_e32 v62, v2
	v_mov_b32_e32 v63, v2
	v_mov_b32_e32 v64, v2
	v_mov_b32_e32 v65, v2
	v_mov_b32_e32 v82, v2
	v_mov_b32_e32 v83, v2
	v_mov_b32_e32 v84, v2
	v_mov_b32_e32 v85, v2
	v_mov_b32_e32 v114, v2
	v_mov_b32_e32 v115, v2
	v_mov_b32_e32 v116, v2
	v_mov_b32_e32 v117, v2
	v_mov_b32_e32 v86, v2
	v_mov_b32_e32 v87, v2
	v_mov_b32_e32 v88, v2
	v_mov_b32_e32 v89, v2
	v_mov_b32_e32 v118, v2
	v_mov_b32_e32 v119, v2
	v_mov_b32_e32 v120, v2
	v_mov_b32_e32 v121, v2
	v_mov_b32_e32 v90, v2
	v_mov_b32_e32 v91, v2
	v_mov_b32_e32 v92, v2
	v_mov_b32_e32 v93, v2
	v_mov_b32_e32 v122, v2
	v_mov_b32_e32 v123, v2
	v_mov_b32_e32 v124, v2
	v_mov_b32_e32 v125, v2
	v_mov_b32_e32 v94, v2
	v_mov_b32_e32 v95, v2
	v_mov_b32_e32 v96, v2
	v_mov_b32_e32 v97, v2
	v_mov_b32_e32 v126, v2
	v_mov_b32_e32 v127, v2
	v_mov_b32_e32 v128, v2
	v_mov_b32_e32 v129, v2
	s_mov_b64 s[46:47], 0x80
	s_add_u32 s12, s10, 0x100
	s_addc_u32 s13, s11, 0
	s_add_i32 s43, 0, 0x10000
	s_cmp_eq_u32 s42, 40
	s_cselect_b32 s17, s3, s13
	s_cselect_b32 s16, s2, s12
	s_cselect_b32 s15, s9, s41
	s_cselect_b32 s14, s8, s36
	s_add_i32 s44, 0, 0x14000
.LBB0_406:
	v_add_u32_e32 v148, s43, v158
	v_add_u32_e32 v168, s44, v158
	ds_read_b128 v[136:139], v148
	ds_read_b128 v[140:143], v148 offset:1024
	ds_read_b128 v[144:147], v148 offset:2048
	ds_read_b128 v[148:151], v148 offset:3072
	ds_read_b128 v[152:155], v168
	ds_read_b128 v[160:163], v168 offset:1024
	ds_read_b128 v[164:167], v168 offset:2048
	ds_read_b128 v[168:171], v168 offset:3072
	v_lshl_add_u64 v[196:197], s[10:11], 0, v[132:133]
	s_add_i32 m0, s21, 0xc000
	ds_read_b128 v[172:175], v159
	ds_read_b128 v[176:179], v159 offset:1024
	ds_read_b128 v[180:183], v159 offset:2048
	ds_read_b128 v[184:187], v159 offset:3072
	ds_read_b128 v[188:191], v159 offset:4096
	ds_read_b128 v[192:195], v159 offset:5120
	ds_read_b128 v[206:209], v159 offset:6144
	ds_read_b128 v[210:213], v159 offset:7168
	global_load_lds_dwordx4 v[196:197], off
	v_lshl_add_u64 v[196:197], s[10:11], 0, v[134:135]
	s_add_i32 m0, s21, 0xe000
	s_nop 0
	global_load_lds_dwordx4 v[196:197], off
	s_waitcnt vmcnt(8)
	s_waitcnt lgkmcnt(0)
	s_barrier
	s_setprio 1
	s_waitcnt lgkmcnt(0)
	v_mfma_f32_16x16x32_bf16 v[126:129], v[136:139], v[172:175], v[126:129]
	v_mfma_f32_16x16x32_bf16 v[94:97], v[144:147], v[172:175], v[94:97]
	v_mfma_f32_16x16x32_bf16 v[122:125], v[136:139], v[180:183], v[122:125]
	v_mfma_f32_16x16x32_bf16 v[90:93], v[144:147], v[180:183], v[90:93]
	v_mfma_f32_16x16x32_bf16 v[118:121], v[136:139], v[188:191], v[118:121]
	v_mfma_f32_16x16x32_bf16 v[86:89], v[144:147], v[188:191], v[86:89]
	v_mfma_f32_16x16x32_bf16 v[114:117], v[136:139], v[206:209], v[114:117]
	v_mfma_f32_16x16x32_bf16 v[82:85], v[144:147], v[206:209], v[82:85]
	v_mfma_f32_16x16x32_bf16 v[126:129], v[140:143], v[176:179], v[126:129]
	v_mfma_f32_16x16x32_bf16 v[94:97], v[148:151], v[176:179], v[94:97]
	v_mfma_f32_16x16x32_bf16 v[122:125], v[140:143], v[184:187], v[122:125]
	v_mfma_f32_16x16x32_bf16 v[90:93], v[148:151], v[184:187], v[90:93]
	v_mfma_f32_16x16x32_bf16 v[118:121], v[140:143], v[192:195], v[118:121]
	v_mfma_f32_16x16x32_bf16 v[86:89], v[148:151], v[192:195], v[86:89]
	v_mfma_f32_16x16x32_bf16 v[114:117], v[140:143], v[210:213], v[114:117]
	v_mfma_f32_16x16x32_bf16 v[82:85], v[148:151], v[210:213], v[82:85]
	s_setprio 0
	s_setprio 1
	v_mfma_f32_16x16x32_bf16 v[62:65], v[152:155], v[172:175], v[62:65]
	v_mfma_f32_16x16x32_bf16 v[30:33], v[164:167], v[172:175], v[30:33]
	v_mfma_f32_16x16x32_bf16 v[58:61], v[152:155], v[180:183], v[58:61]
	v_mfma_f32_16x16x32_bf16 v[26:29], v[164:167], v[180:183], v[26:29]
	v_mfma_f32_16x16x32_bf16 v[54:57], v[152:155], v[188:191], v[54:57]
	v_mfma_f32_16x16x32_bf16 v[22:25], v[164:167], v[188:191], v[22:25]
	v_mfma_f32_16x16x32_bf16 v[50:53], v[152:155], v[206:209], v[50:53]
	v_mfma_f32_16x16x32_bf16 v[18:21], v[164:167], v[206:209], v[18:21]
	v_mfma_f32_16x16x32_bf16 v[62:65], v[160:163], v[176:179], v[62:65]
	v_mfma_f32_16x16x32_bf16 v[30:33], v[168:171], v[176:179], v[30:33]
	v_mfma_f32_16x16x32_bf16 v[58:61], v[160:163], v[184:187], v[58:61]
	v_mfma_f32_16x16x32_bf16 v[26:29], v[168:171], v[184:187], v[26:29]
	v_mfma_f32_16x16x32_bf16 v[54:57], v[160:163], v[192:195], v[54:57]
	v_mfma_f32_16x16x32_bf16 v[22:25], v[168:171], v[192:195], v[22:25]
	v_mfma_f32_16x16x32_bf16 v[50:53], v[160:163], v[210:213], v[50:53]
	v_mfma_f32_16x16x32_bf16 v[18:21], v[168:171], v[210:213], v[18:21]
	s_setprio 0
	s_barrier
	s_add_i32 s10, s43, s63
	v_lshl_add_u64 v[196:197], s[14:15], 0, v[0:1]
	s_mov_b32 m0, s10
	ds_read_b128 v[172:175], v159 offset:16384
	ds_read_b128 v[176:179], v159 offset:17408
	ds_read_b128 v[180:183], v159 offset:18432
	ds_read_b128 v[184:187], v159 offset:19456
	ds_read_b128 v[188:191], v159 offset:20480
	ds_read_b128 v[192:195], v159 offset:21504
	ds_read_b128 v[206:209], v159 offset:22528
	ds_read_b128 v[210:213], v159 offset:23552
	global_load_lds_dwordx4 v[196:197], off
	s_add_i32 m0, s10, 0x2000
	s_add_u32 s10, s14, 0xb0000
	v_lshl_add_u64 v[214:215], s[14:15], 0, v[130:131]
	s_addc_u32 s11, s15, 0
	s_add_i32 s43, s44, s63
	global_load_lds_dwordx4 v[214:215], off
	v_lshl_add_u64 v[216:217], s[10:11], 0, v[0:1]
	s_mov_b32 m0, s43
	v_lshl_add_u64 v[218:219], s[16:17], 0, v[130:131]
	global_load_lds_dwordx4 v[216:217], off
	v_lshl_add_u64 v[216:217], s[10:11], 0, v[130:131]
	s_add_i32 m0, s43, 0x2000
	s_nop 0
	global_load_lds_dwordx4 v[216:217], off
	v_lshl_add_u64 v[216:217], s[16:17], 0, v[0:1]
	s_mov_b32 m0, s21
	s_nop 0
	global_load_lds_dwordx4 v[216:217], off
	s_mov_b32 m0, s22
	s_nop 0
	global_load_lds_dwordx4 v[218:219], off
	s_waitcnt vmcnt(8)
	s_waitcnt lgkmcnt(0)
	s_barrier
	s_setprio 1
	s_waitcnt lgkmcnt(0)
	v_mfma_f32_16x16x32_bf16 v[110:113], v[136:139], v[172:175], v[110:113]
	v_mfma_f32_16x16x32_bf16 v[78:81], v[144:147], v[172:175], v[78:81]
	v_mfma_f32_16x16x32_bf16 v[106:109], v[136:139], v[180:183], v[106:109]
	v_mfma_f32_16x16x32_bf16 v[74:77], v[144:147], v[180:183], v[74:77]
	v_mfma_f32_16x16x32_bf16 v[102:105], v[136:139], v[188:191], v[102:105]
	v_mfma_f32_16x16x32_bf16 v[70:73], v[144:147], v[188:191], v[70:73]
	v_mfma_f32_16x16x32_bf16 v[98:101], v[136:139], v[206:209], v[98:101]
	v_mfma_f32_16x16x32_bf16 v[66:69], v[144:147], v[206:209], v[66:69]
	v_mfma_f32_16x16x32_bf16 v[110:113], v[140:143], v[176:179], v[110:113]
	v_mfma_f32_16x16x32_bf16 v[78:81], v[148:151], v[176:179], v[78:81]
	v_mfma_f32_16x16x32_bf16 v[106:109], v[140:143], v[184:187], v[106:109]
	v_mfma_f32_16x16x32_bf16 v[74:77], v[148:151], v[184:187], v[74:77]
	v_mfma_f32_16x16x32_bf16 v[102:105], v[140:143], v[192:195], v[102:105]
	v_mfma_f32_16x16x32_bf16 v[70:73], v[148:151], v[192:195], v[70:73]
	v_mfma_f32_16x16x32_bf16 v[98:101], v[140:143], v[210:213], v[98:101]
	v_mfma_f32_16x16x32_bf16 v[66:69], v[148:151], v[210:213], v[66:69]
	s_setprio 0
	s_setprio 1
	v_mfma_f32_16x16x32_bf16 v[46:49], v[152:155], v[172:175], v[46:49]
	v_mfma_f32_16x16x32_bf16 v[14:17], v[164:167], v[172:175], v[14:17]
	v_mfma_f32_16x16x32_bf16 v[42:45], v[152:155], v[180:183], v[42:45]
	v_mfma_f32_16x16x32_bf16 v[10:13], v[164:167], v[180:183], v[10:13]
	v_mfma_f32_16x16x32_bf16 v[38:41], v[152:155], v[188:191], v[38:41]
	v_mfma_f32_16x16x32_bf16 v[6:9], v[164:167], v[188:191], v[6:9]
	v_mfma_f32_16x16x32_bf16 v[34:37], v[152:155], v[206:209], v[34:37]
	v_mfma_f32_16x16x32_bf16 v[2:5], v[164:167], v[206:209], v[2:5]
	v_mfma_f32_16x16x32_bf16 v[46:49], v[160:163], v[176:179], v[46:49]
	v_mfma_f32_16x16x32_bf16 v[14:17], v[168:171], v[176:179], v[14:17]
	v_mfma_f32_16x16x32_bf16 v[42:45], v[160:163], v[184:187], v[42:45]
	v_mfma_f32_16x16x32_bf16 v[10:13], v[168:171], v[184:187], v[10:13]
	v_mfma_f32_16x16x32_bf16 v[38:41], v[160:163], v[192:195], v[38:41]
	v_mfma_f32_16x16x32_bf16 v[6:9], v[168:171], v[192:195], v[6:9]
	v_mfma_f32_16x16x32_bf16 v[34:37], v[160:163], v[210:213], v[34:37]
	v_mfma_f32_16x16x32_bf16 v[2:5], v[168:171], v[210:213], v[2:5]
	s_setprio 0
	s_barrier
	s_add_i32 s43, 0, 0x18000
	s_add_i32 s44, 0, 0x1c000
	v_add_u32_e32 v148, s43, v158
	v_add_u32_e32 v168, s44, v158
	ds_read_b128 v[136:139], v148
	ds_read_b128 v[140:143], v148 offset:1024
	ds_read_b128 v[144:147], v148 offset:2048
	ds_read_b128 v[148:151], v148 offset:3072
	ds_read_b128 v[152:155], v168
	ds_read_b128 v[160:163], v168 offset:1024
	ds_read_b128 v[164:167], v168 offset:2048
	ds_read_b128 v[168:171], v168 offset:3072
	s_add_u32 s10, s16, 0xb0000
	s_addc_u32 s11, s17, 0
	s_mov_b32 m0, s23
	v_lshl_add_u64 v[220:221], s[10:11], 0, v[0:1]
	ds_read_b128 v[172:175], v159 offset:32768
	ds_read_b128 v[176:179], v159 offset:33792
	ds_read_b128 v[180:183], v159 offset:34816
	ds_read_b128 v[184:187], v159 offset:35840
	ds_read_b128 v[188:191], v159 offset:36864
	ds_read_b128 v[192:195], v159 offset:37888
	ds_read_b128 v[206:209], v159 offset:38912
	ds_read_b128 v[210:213], v159 offset:39936
	global_load_lds_dwordx4 v[220:221], off
	v_lshl_add_u64 v[220:221], s[10:11], 0, v[130:131]
	s_mov_b32 m0, s24
	s_nop 0
	global_load_lds_dwordx4 v[220:221], off
	s_waitcnt vmcnt(8)
	s_waitcnt lgkmcnt(0)
	s_barrier
	s_setprio 1
	s_waitcnt lgkmcnt(0)
	v_mfma_f32_16x16x32_bf16 v[126:129], v[136:139], v[172:175], v[126:129]
	v_mfma_f32_16x16x32_bf16 v[94:97], v[144:147], v[172:175], v[94:97]
	v_mfma_f32_16x16x32_bf16 v[122:125], v[136:139], v[180:183], v[122:125]
	v_mfma_f32_16x16x32_bf16 v[90:93], v[144:147], v[180:183], v[90:93]
	v_mfma_f32_16x16x32_bf16 v[118:121], v[136:139], v[188:191], v[118:121]
	v_mfma_f32_16x16x32_bf16 v[86:89], v[144:147], v[188:191], v[86:89]
	v_mfma_f32_16x16x32_bf16 v[114:117], v[136:139], v[206:209], v[114:117]
	v_mfma_f32_16x16x32_bf16 v[82:85], v[144:147], v[206:209], v[82:85]
	v_mfma_f32_16x16x32_bf16 v[126:129], v[140:143], v[176:179], v[126:129]
	v_mfma_f32_16x16x32_bf16 v[94:97], v[148:151], v[176:179], v[94:97]
	v_mfma_f32_16x16x32_bf16 v[122:125], v[140:143], v[184:187], v[122:125]
	v_mfma_f32_16x16x32_bf16 v[90:93], v[148:151], v[184:187], v[90:93]
	v_mfma_f32_16x16x32_bf16 v[118:121], v[140:143], v[192:195], v[118:121]
	v_mfma_f32_16x16x32_bf16 v[86:89], v[148:151], v[192:195], v[86:89]
	v_mfma_f32_16x16x32_bf16 v[114:117], v[140:143], v[210:213], v[114:117]
	v_mfma_f32_16x16x32_bf16 v[82:85], v[148:151], v[210:213], v[82:85]
	s_setprio 0
	s_setprio 1
	v_mfma_f32_16x16x32_bf16 v[62:65], v[152:155], v[172:175], v[62:65]
	v_mfma_f32_16x16x32_bf16 v[30:33], v[164:167], v[172:175], v[30:33]
	v_mfma_f32_16x16x32_bf16 v[58:61], v[152:155], v[180:183], v[58:61]
	v_mfma_f32_16x16x32_bf16 v[26:29], v[164:167], v[180:183], v[26:29]
	v_mfma_f32_16x16x32_bf16 v[54:57], v[152:155], v[188:191], v[54:57]
	v_mfma_f32_16x16x32_bf16 v[22:25], v[164:167], v[188:191], v[22:25]
	v_mfma_f32_16x16x32_bf16 v[50:53], v[152:155], v[206:209], v[50:53]
	v_mfma_f32_16x16x32_bf16 v[18:21], v[164:167], v[206:209], v[18:21]
	v_mfma_f32_16x16x32_bf16 v[62:65], v[160:163], v[176:179], v[62:65]
	v_mfma_f32_16x16x32_bf16 v[30:33], v[168:171], v[176:179], v[30:33]
	v_mfma_f32_16x16x32_bf16 v[58:61], v[160:163], v[184:187], v[58:61]
	v_mfma_f32_16x16x32_bf16 v[26:29], v[168:171], v[184:187], v[26:29]
	v_mfma_f32_16x16x32_bf16 v[54:57], v[160:163], v[192:195], v[54:57]
	v_mfma_f32_16x16x32_bf16 v[22:25], v[168:171], v[192:195], v[22:25]
	v_mfma_f32_16x16x32_bf16 v[50:53], v[160:163], v[210:213], v[50:53]
	v_mfma_f32_16x16x32_bf16 v[18:21], v[168:171], v[210:213], v[18:21]
	s_setprio 0
	s_barrier
	s_add_i32 s10, s43, s63
	v_lshl_add_u64 v[196:197], v[196:197], 0, s[46:47]
	s_mov_b32 m0, s10
	ds_read_b128 v[172:175], v159 offset:49152
	ds_read_b128 v[176:179], v159 offset:50176
	ds_read_b128 v[180:183], v159 offset:51200
	ds_read_b128 v[184:187], v159 offset:52224
	ds_read_b128 v[188:191], v159 offset:53248
	ds_read_b128 v[192:195], v159 offset:54272
	ds_read_b128 v[206:209], v159 offset:55296
	ds_read_b128 v[210:213], v159 offset:56320
	global_load_lds_dwordx4 v[196:197], off
	s_add_i32 m0, s10, 0x2000
	s_add_u32 s10, s14, 0xb0080
	v_lshl_add_u64 v[196:197], v[214:215], 0, s[46:47]
	s_addc_u32 s11, s15, 0
	s_add_i32 s14, s44, s63
	global_load_lds_dwordx4 v[196:197], off
	v_lshl_add_u64 v[196:197], s[10:11], 0, v[0:1]
	s_mov_b32 m0, s14
	s_nop 0
	global_load_lds_dwordx4 v[196:197], off
	v_lshl_add_u64 v[196:197], s[10:11], 0, v[130:131]
	s_add_i32 m0, s14, 0x2000
	s_nop 0
	global_load_lds_dwordx4 v[196:197], off
	v_lshl_add_u64 v[196:197], v[216:217], 0, s[46:47]
	s_mov_b32 m0, s27
	s_nop 0
	global_load_lds_dwordx4 v[196:197], off
	v_lshl_add_u64 v[196:197], v[218:219], 0, s[46:47]
	s_mov_b32 m0, s28
	s_nop 0
	global_load_lds_dwordx4 v[196:197], off
	s_waitcnt vmcnt(8)
	s_waitcnt lgkmcnt(0)
	s_barrier
	s_setprio 1
	s_waitcnt lgkmcnt(0)
	v_mfma_f32_16x16x32_bf16 v[110:113], v[136:139], v[172:175], v[110:113]
	v_mfma_f32_16x16x32_bf16 v[78:81], v[144:147], v[172:175], v[78:81]
	v_mfma_f32_16x16x32_bf16 v[106:109], v[136:139], v[180:183], v[106:109]
	v_mfma_f32_16x16x32_bf16 v[74:77], v[144:147], v[180:183], v[74:77]
	v_mfma_f32_16x16x32_bf16 v[102:105], v[136:139], v[188:191], v[102:105]
	v_mfma_f32_16x16x32_bf16 v[70:73], v[144:147], v[188:191], v[70:73]
	v_mfma_f32_16x16x32_bf16 v[98:101], v[136:139], v[206:209], v[98:101]
	v_mfma_f32_16x16x32_bf16 v[66:69], v[144:147], v[206:209], v[66:69]
	v_mfma_f32_16x16x32_bf16 v[110:113], v[140:143], v[176:179], v[110:113]
	v_mfma_f32_16x16x32_bf16 v[78:81], v[148:151], v[176:179], v[78:81]
	v_mfma_f32_16x16x32_bf16 v[106:109], v[140:143], v[184:187], v[106:109]
	v_mfma_f32_16x16x32_bf16 v[74:77], v[148:151], v[184:187], v[74:77]
	v_mfma_f32_16x16x32_bf16 v[102:105], v[140:143], v[192:195], v[102:105]
	v_mfma_f32_16x16x32_bf16 v[70:73], v[148:151], v[192:195], v[70:73]
	v_mfma_f32_16x16x32_bf16 v[98:101], v[140:143], v[210:213], v[98:101]
	v_mfma_f32_16x16x32_bf16 v[66:69], v[148:151], v[210:213], v[66:69]
	s_setprio 0
	s_setprio 1
	v_mfma_f32_16x16x32_bf16 v[46:49], v[152:155], v[172:175], v[46:49]
	v_mfma_f32_16x16x32_bf16 v[14:17], v[164:167], v[172:175], v[14:17]
	v_mfma_f32_16x16x32_bf16 v[42:45], v[152:155], v[180:183], v[42:45]
	v_mfma_f32_16x16x32_bf16 v[10:13], v[164:167], v[180:183], v[10:13]
	v_mfma_f32_16x16x32_bf16 v[38:41], v[152:155], v[188:191], v[38:41]
	v_mfma_f32_16x16x32_bf16 v[6:9], v[164:167], v[188:191], v[6:9]
	v_mfma_f32_16x16x32_bf16 v[34:37], v[152:155], v[206:209], v[34:37]
	v_mfma_f32_16x16x32_bf16 v[2:5], v[164:167], v[206:209], v[2:5]
	v_mfma_f32_16x16x32_bf16 v[46:49], v[160:163], v[176:179], v[46:49]
	v_mfma_f32_16x16x32_bf16 v[14:17], v[168:171], v[176:179], v[14:17]
	v_mfma_f32_16x16x32_bf16 v[42:45], v[160:163], v[184:187], v[42:45]
	v_mfma_f32_16x16x32_bf16 v[10:13], v[168:171], v[184:187], v[10:13]
	v_mfma_f32_16x16x32_bf16 v[38:41], v[160:163], v[192:195], v[38:41]
	v_mfma_f32_16x16x32_bf16 v[6:9], v[168:171], v[192:195], v[6:9]
	v_mfma_f32_16x16x32_bf16 v[34:37], v[160:163], v[210:213], v[34:37]
	v_mfma_f32_16x16x32_bf16 v[2:5], v[168:171], v[210:213], v[2:5]
	s_setprio 0
	s_add_i32 s42, s42, 2
	s_add_u32 s36, s36, 0x100
	s_addc_u32 s41, s41, 0
	s_mov_b64 s[10:11], s[12:13]
	s_add_u32 s12, s10, 0x100
	s_addc_u32 s13, s11, 0
	s_add_i32 s43, 0, 0x10000
	s_cmp_eq_u32 s42, 40
	s_cselect_b32 s17, s3, s13
	s_cselect_b32 s16, s2, s12
	s_cselect_b32 s15, s9, s41
	s_cselect_b32 s14, s8, s36
	s_add_i32 s44, 0, 0x14000
	s_cmp_gt_u32 s42, 41
	s_barrier
	s_cbranch_scc0 .LBB0_406
	v_readlane_b32 s10, v253, 25
	v_readlane_b32 s11, v253, 26
	s_and_b64 vcc, exec, s[10:11]
	s_cbranch_vccz .LBB0_409
	s_barrier

.LBB0_477:
	s_ashr_i32 s29, s28, 31
	s_lshl_b64 s[2:3], s[28:29], 19
	v_readlane_b32 s10, v254, 43
	v_readlane_b32 s11, v254, 44
	s_add_u32 s24, s10, s2
	s_addc_u32 s25, s11, s3
	s_and_b64 s[2:3], s[6:7], exec
	s_cselect_b32 s1, s25, s9
	s_cselect_b32 s12, s24, s8
	s_ashr_i32 s27, s26, 31
	s_lshl_b64 s[2:3], s[26:27], 19
	s_add_u32 s2, s34, s2
	s_addc_u32 s3, s35, s3
	s_and_b64 s[10:11], s[6:7], exec
	s_cselect_b32 s13, s3, s5
	s_cselect_b32 s14, s2, s4
	s_add_u32 s8, s8, 0x40080
	s_addc_u32 s9, s9, 0
	s_add_u32 s15, s4, 0x100
	v_mov_b32_e32 v6, 0
	s_addc_u32 s16, s5, 0
	s_mov_b32 s17, -2
	v_mov_b32_e32 v7, v6
	v_mov_b32_e32 v8, v6
	v_mov_b32_e32 v9, v6
	v_mov_b32_e32 v2, v6
	v_mov_b32_e32 v3, v6
	v_mov_b32_e32 v4, v6
	v_mov_b32_e32 v5, v6
	v_mov_b32_e32 v14, v6
	v_mov_b32_e32 v15, v6
	v_mov_b32_e32 v16, v6
	v_mov_b32_e32 v17, v6
	v_mov_b32_e32 v10, v6
	v_mov_b32_e32 v11, v6
	v_mov_b32_e32 v12, v6
	v_mov_b32_e32 v13, v6
	v_mov_b32_e32 v22, v6
	v_mov_b32_e32 v23, v6
	v_mov_b32_e32 v24, v6
	v_mov_b32_e32 v25, v6
	v_mov_b32_e32 v18, v6
	v_mov_b32_e32 v19, v6
	v_mov_b32_e32 v20, v6
	v_mov_b32_e32 v21, v6
	v_mov_b32_e32 v30, v6
	v_mov_b32_e32 v31, v6
	v_mov_b32_e32 v32, v6
	v_mov_b32_e32 v33, v6
	v_mov_b32_e32 v26, v6
	v_mov_b32_e32 v27, v6
	v_mov_b32_e32 v28, v6
	v_mov_b32_e32 v29, v6
	s_waitcnt vmcnt(0)
	v_mov_b32_e32 v70, v6
	v_mov_b32_e32 v71, v6
	v_mov_b32_e32 v72, v6
	v_mov_b32_e32 v73, v6
	v_mov_b32_e32 v66, v6
	v_mov_b32_e32 v67, v6
	v_mov_b32_e32 v68, v6
	v_mov_b32_e32 v69, v6
	v_mov_b32_e32 v78, v6
	v_mov_b32_e32 v79, v6
	s_waitcnt lgkmcnt(0)
	v_mov_b32_e32 v80, v6
	v_mov_b32_e32 v81, v6
	v_mov_b32_e32 v74, v6
	v_mov_b32_e32 v75, v6
	v_mov_b32_e32 v76, v6
	v_mov_b32_e32 v77, v6
	v_mov_b32_e32 v102, v6
	v_mov_b32_e32 v103, v6
	v_mov_b32_e32 v104, v6
	v_mov_b32_e32 v105, v6
	v_mov_b32_e32 v98, v6
	v_mov_b32_e32 v99, v6
	v_mov_b32_e32 v100, v6
	v_mov_b32_e32 v101, v6
	v_mov_b32_e32 v126, v6
	v_mov_b32_e32 v127, v6
	v_mov_b32_e32 v128, v6
	v_mov_b32_e32 v129, v6
	v_mov_b32_e32 v122, v6
	v_mov_b32_e32 v123, v6
	v_mov_b32_e32 v124, v6
	v_mov_b32_e32 v125, v6
	v_mov_b32_e32 v38, v6
	v_mov_b32_e32 v39, v6
	v_mov_b32_e32 v40, v6
	v_mov_b32_e32 v41, v6
	v_mov_b32_e32 v34, v6
	v_mov_b32_e32 v35, v6
	v_mov_b32_e32 v36, v6
	v_mov_b32_e32 v37, v6
	v_mov_b32_e32 v46, v6
	v_mov_b32_e32 v47, v6
	v_mov_b32_e32 v48, v6
	v_mov_b32_e32 v49, v6
	v_mov_b32_e32 v42, v6
	v_mov_b32_e32 v43, v6
	v_mov_b32_e32 v44, v6
	v_mov_b32_e32 v45, v6
	v_mov_b32_e32 v54, v6
	v_mov_b32_e32 v55, v6
	v_mov_b32_e32 v56, v6
	v_mov_b32_e32 v57, v6
	v_mov_b32_e32 v50, v6
	v_mov_b32_e32 v51, v6
	v_mov_b32_e32 v52, v6
	v_mov_b32_e32 v53, v6
	v_mov_b32_e32 v62, v6
	v_mov_b32_e32 v63, v6
	v_mov_b32_e32 v64, v6
	v_mov_b32_e32 v65, v6
	v_mov_b32_e32 v58, v6
	v_mov_b32_e32 v59, v6
	v_mov_b32_e32 v60, v6
	v_mov_b32_e32 v61, v6
	v_mov_b32_e32 v166, v6
	v_mov_b32_e32 v167, v6
	v_mov_b32_e32 v168, v6
	v_mov_b32_e32 v169, v6
	v_mov_b32_e32 v146, v6
	v_mov_b32_e32 v147, v6
	v_mov_b32_e32 v148, v6
	v_mov_b32_e32 v149, v6
	v_mov_b32_e32 v174, v6
	v_mov_b32_e32 v175, v6
	v_mov_b32_e32 v176, v6
	v_mov_b32_e32 v177, v6
	v_mov_b32_e32 v170, v6
	v_mov_b32_e32 v171, v6
	v_mov_b32_e32 v172, v6
	v_mov_b32_e32 v173, v6
	v_mov_b32_e32 v182, v6
	v_mov_b32_e32 v183, v6
	v_mov_b32_e32 v184, v6
	v_mov_b32_e32 v185, v6
	v_mov_b32_e32 v178, v6
	v_mov_b32_e32 v179, v6
	v_mov_b32_e32 v180, v6
	v_mov_b32_e32 v181, v6
	v_mov_b32_e32 v190, v6
	v_mov_b32_e32 v191, v6
	v_mov_b32_e32 v192, v6
	v_mov_b32_e32 v193, v6
	v_mov_b32_e32 v186, v6
	v_mov_b32_e32 v187, v6
	v_mov_b32_e32 v188, v6
	v_mov_b32_e32 v189, v6
	s_mov_b64 s[30:31], 0x80
	s_add_u32 s4, s8, 0xfffc0080
	s_addc_u32 s5, s9, -1
	s_add_i32 s18, 0, 0x10000
	s_cmp_eq_u32 s17, 12
	s_cselect_b32 s11, s1, s5
	s_cselect_b32 s10, s12, s4
	s_cselect_b32 s5, s13, s16
	s_cselect_b32 s4, s14, s15
	s_add_i32 s23, 0, 0x14000
.LBB0_478:
	v_add_u32_e32 v0, s18, v243
	ds_read_b128 v[82:85], v0
	ds_read_b128 v[86:89], v0 offset:1024
	ds_read_b128 v[90:93], v0 offset:2048
	ds_read_b128 v[94:97], v0 offset:3072
	v_add_u32_e32 v0, s23, v243
	ds_read_b128 v[106:109], v0
	ds_read_b128 v[110:113], v0 offset:1024
	ds_read_b128 v[114:117], v0 offset:2048
	ds_read_b128 v[118:121], v0 offset:3072
	v_lshl_add_u64 v[194:195], s[8:9], 0, v[214:215]
	s_add_i32 m0, s36, 0xc000
	ds_read_b128 v[130:133], v244
	ds_read_b128 v[134:137], v244 offset:1024
	ds_read_b128 v[138:141], v244 offset:2048
	ds_read_b128 v[142:145], v244 offset:3072
	ds_read_b128 v[150:153], v244 offset:4096
	ds_read_b128 v[154:157], v244 offset:5120
	ds_read_b128 v[158:161], v244 offset:6144
	ds_read_b128 v[162:165], v244 offset:7168
	global_load_lds_dwordx4 v[194:195], off
	v_lshl_add_u64 v[194:195], s[8:9], 0, v[216:217]
	s_add_i32 m0, s36, 0xe000
	s_nop 0
	global_load_lds_dwordx4 v[194:195], off
	s_waitcnt vmcnt(8)
	s_waitcnt lgkmcnt(0)
	s_barrier
	s_setprio 1
	s_waitcnt lgkmcnt(0)
	v_mfma_f32_16x16x32_bf16 v[186:189], v[82:85], v[130:133], v[186:189]
	v_mfma_f32_16x16x32_bf16 v[190:193], v[90:93], v[130:133], v[190:193]
	v_mfma_f32_16x16x32_bf16 v[178:181], v[82:85], v[138:141], v[178:181]
	v_mfma_f32_16x16x32_bf16 v[182:185], v[90:93], v[138:141], v[182:185]
	v_mfma_f32_16x16x32_bf16 v[170:173], v[82:85], v[150:153], v[170:173]
	v_mfma_f32_16x16x32_bf16 v[174:177], v[90:93], v[150:153], v[174:177]
	v_mfma_f32_16x16x32_bf16 v[146:149], v[82:85], v[158:161], v[146:149]
	v_mfma_f32_16x16x32_bf16 v[166:169], v[90:93], v[158:161], v[166:169]
	v_mfma_f32_16x16x32_bf16 v[186:189], v[86:89], v[134:137], v[186:189]
	v_mfma_f32_16x16x32_bf16 v[190:193], v[94:97], v[134:137], v[190:193]
	v_mfma_f32_16x16x32_bf16 v[178:181], v[86:89], v[142:145], v[178:181]
	v_mfma_f32_16x16x32_bf16 v[182:185], v[94:97], v[142:145], v[182:185]
	v_mfma_f32_16x16x32_bf16 v[170:173], v[86:89], v[154:157], v[170:173]
	v_mfma_f32_16x16x32_bf16 v[174:177], v[94:97], v[154:157], v[174:177]
	v_mfma_f32_16x16x32_bf16 v[146:149], v[86:89], v[162:165], v[146:149]
	v_mfma_f32_16x16x32_bf16 v[166:169], v[94:97], v[162:165], v[166:169]
	s_setprio 0
	s_setprio 1
	v_mfma_f32_16x16x32_bf16 v[58:61], v[106:109], v[130:133], v[58:61]
	v_mfma_f32_16x16x32_bf16 v[62:65], v[114:117], v[130:133], v[62:65]
	v_mfma_f32_16x16x32_bf16 v[50:53], v[106:109], v[138:141], v[50:53]
	v_mfma_f32_16x16x32_bf16 v[54:57], v[114:117], v[138:141], v[54:57]
	v_mfma_f32_16x16x32_bf16 v[42:45], v[106:109], v[150:153], v[42:45]
	v_mfma_f32_16x16x32_bf16 v[46:49], v[114:117], v[150:153], v[46:49]
	v_mfma_f32_16x16x32_bf16 v[34:37], v[106:109], v[158:161], v[34:37]
	v_mfma_f32_16x16x32_bf16 v[38:41], v[114:117], v[158:161], v[38:41]
	v_mfma_f32_16x16x32_bf16 v[58:61], v[110:113], v[134:137], v[58:61]
	v_mfma_f32_16x16x32_bf16 v[62:65], v[118:121], v[134:137], v[62:65]
	v_mfma_f32_16x16x32_bf16 v[50:53], v[110:113], v[142:145], v[50:53]
	v_mfma_f32_16x16x32_bf16 v[54:57], v[118:121], v[142:145], v[54:57]
	v_mfma_f32_16x16x32_bf16 v[42:45], v[110:113], v[154:157], v[42:45]
	v_mfma_f32_16x16x32_bf16 v[46:49], v[118:121], v[154:157], v[46:49]
	v_mfma_f32_16x16x32_bf16 v[34:37], v[110:113], v[162:165], v[34:37]
	v_mfma_f32_16x16x32_bf16 v[38:41], v[118:121], v[162:165], v[38:41]
	s_setprio 0
	s_barrier
	s_add_i32 s18, s18, s63
	v_lshl_add_u64 v[194:195], s[4:5], 0, v[208:209]
	s_mov_b32 m0, s18
	ds_read_b128 v[130:133], v244 offset:16384
	ds_read_b128 v[134:137], v244 offset:17408
	ds_read_b128 v[138:141], v244 offset:18432
	ds_read_b128 v[142:145], v244 offset:19456
	ds_read_b128 v[150:153], v244 offset:20480
	ds_read_b128 v[154:157], v244 offset:21504
	ds_read_b128 v[158:161], v244 offset:22528
	ds_read_b128 v[162:165], v244 offset:23552
	global_load_lds_dwordx4 v[194:195], off
	s_add_i32 m0, s18, 0x2000
	s_add_u32 s18, s4, 0x40000
	v_lshl_add_u64 v[196:197], s[4:5], 0, v[212:213]
	s_addc_u32 s19, s5, 0
	s_add_i32 s23, s23, s63
	global_load_lds_dwordx4 v[196:197], off
	v_lshl_add_u64 v[218:219], s[18:19], 0, v[208:209]
	s_mov_b32 m0, s23
	v_lshl_add_u64 v[220:221], s[10:11], 0, v[210:211]
	global_load_lds_dwordx4 v[218:219], off
	v_lshl_add_u64 v[218:219], s[18:19], 0, v[212:213]
	s_add_i32 m0, s23, 0x2000
	s_nop 0
	global_load_lds_dwordx4 v[218:219], off
	v_lshl_add_u64 v[218:219], s[10:11], 0, v[206:207]
	s_mov_b32 m0, s36
	s_nop 0
	global_load_lds_dwordx4 v[218:219], off
	s_mov_b32 m0, s40
	s_nop 0
	global_load_lds_dwordx4 v[220:221], off
	s_waitcnt vmcnt(8)
	s_waitcnt lgkmcnt(0)
	s_barrier
	s_setprio 1
	s_waitcnt lgkmcnt(0)
	v_mfma_f32_16x16x32_bf16 v[122:125], v[82:85], v[130:133], v[122:125]
	v_mfma_f32_16x16x32_bf16 v[126:129], v[90:93], v[130:133], v[126:129]
	v_mfma_f32_16x16x32_bf16 v[98:101], v[82:85], v[138:141], v[98:101]
	v_mfma_f32_16x16x32_bf16 v[102:105], v[90:93], v[138:141], v[102:105]
	v_mfma_f32_16x16x32_bf16 v[74:77], v[82:85], v[150:153], v[74:77]
	v_mfma_f32_16x16x32_bf16 v[78:81], v[90:93], v[150:153], v[78:81]
	v_mfma_f32_16x16x32_bf16 v[66:69], v[82:85], v[158:161], v[66:69]
	v_mfma_f32_16x16x32_bf16 v[70:73], v[90:93], v[158:161], v[70:73]
	v_mfma_f32_16x16x32_bf16 v[122:125], v[86:89], v[134:137], v[122:125]
	v_mfma_f32_16x16x32_bf16 v[126:129], v[94:97], v[134:137], v[126:129]
	v_mfma_f32_16x16x32_bf16 v[98:101], v[86:89], v[142:145], v[98:101]
	v_mfma_f32_16x16x32_bf16 v[102:105], v[94:97], v[142:145], v[102:105]
	v_mfma_f32_16x16x32_bf16 v[74:77], v[86:89], v[154:157], v[74:77]
	v_mfma_f32_16x16x32_bf16 v[78:81], v[94:97], v[154:157], v[78:81]
	v_mfma_f32_16x16x32_bf16 v[66:69], v[86:89], v[162:165], v[66:69]
	v_mfma_f32_16x16x32_bf16 v[70:73], v[94:97], v[162:165], v[70:73]
	s_setprio 0
	s_setprio 1
	v_mfma_f32_16x16x32_bf16 v[26:29], v[106:109], v[130:133], v[26:29]
	v_mfma_f32_16x16x32_bf16 v[30:33], v[114:117], v[130:133], v[30:33]
	v_mfma_f32_16x16x32_bf16 v[18:21], v[106:109], v[138:141], v[18:21]
	v_mfma_f32_16x16x32_bf16 v[22:25], v[114:117], v[138:141], v[22:25]
	v_mfma_f32_16x16x32_bf16 v[10:13], v[106:109], v[150:153], v[10:13]
	v_mfma_f32_16x16x32_bf16 v[14:17], v[114:117], v[150:153], v[14:17]
	v_mfma_f32_16x16x32_bf16 v[2:5], v[106:109], v[158:161], v[2:5]
	v_mfma_f32_16x16x32_bf16 v[6:9], v[114:117], v[158:161], v[6:9]
	v_mfma_f32_16x16x32_bf16 v[26:29], v[110:113], v[134:137], v[26:29]
	v_mfma_f32_16x16x32_bf16 v[30:33], v[118:121], v[134:137], v[30:33]
	v_mfma_f32_16x16x32_bf16 v[18:21], v[110:113], v[142:145], v[18:21]
	v_mfma_f32_16x16x32_bf16 v[22:25], v[118:121], v[142:145], v[22:25]
	v_mfma_f32_16x16x32_bf16 v[10:13], v[110:113], v[154:157], v[10:13]
	v_mfma_f32_16x16x32_bf16 v[14:17], v[118:121], v[154:157], v[14:17]
	v_mfma_f32_16x16x32_bf16 v[2:5], v[110:113], v[162:165], v[2:5]
	v_mfma_f32_16x16x32_bf16 v[6:9], v[118:121], v[162:165], v[6:9]
	s_setprio 0
	s_barrier
	s_add_i32 s18, 0, 0x18000
	v_add_u32_e32 v0, s18, v243
	s_add_i32 s19, 0, 0x1c000
	ds_read_b128 v[82:85], v0
	ds_read_b128 v[86:89], v0 offset:1024
	ds_read_b128 v[90:93], v0 offset:2048
	ds_read_b128 v[94:97], v0 offset:3072
	v_add_u32_e32 v0, s19, v243
	ds_read_b128 v[106:109], v0
	ds_read_b128 v[110:113], v0 offset:1024
	ds_read_b128 v[114:117], v0 offset:2048
	ds_read_b128 v[118:121], v0 offset:3072
	s_add_u32 s10, s10, 0x40000
	s_addc_u32 s11, s11, 0
	s_mov_b32 m0, s41
	v_lshl_add_u64 v[222:223], s[10:11], 0, v[206:207]
	ds_read_b128 v[130:133], v244 offset:32768
	ds_read_b128 v[134:137], v244 offset:33792
	ds_read_b128 v[138:141], v244 offset:34816
	ds_read_b128 v[142:145], v244 offset:35840
	ds_read_b128 v[150:153], v244 offset:36864
	ds_read_b128 v[154:157], v244 offset:37888
	ds_read_b128 v[158:161], v244 offset:38912
	ds_read_b128 v[162:165], v244 offset:39936
	global_load_lds_dwordx4 v[222:223], off
	v_lshl_add_u64 v[222:223], s[10:11], 0, v[210:211]
	s_mov_b32 m0, s44
	s_nop 0
	global_load_lds_dwordx4 v[222:223], off
	s_waitcnt vmcnt(8)
	s_waitcnt lgkmcnt(0)
	s_barrier
	s_setprio 1
	s_waitcnt lgkmcnt(0)
	v_mfma_f32_16x16x32_bf16 v[186:189], v[82:85], v[130:133], v[186:189]
	v_mfma_f32_16x16x32_bf16 v[190:193], v[90:93], v[130:133], v[190:193]
	v_mfma_f32_16x16x32_bf16 v[178:181], v[82:85], v[138:141], v[178:181]
	v_mfma_f32_16x16x32_bf16 v[182:185], v[90:93], v[138:141], v[182:185]
	v_mfma_f32_16x16x32_bf16 v[170:173], v[82:85], v[150:153], v[170:173]
	v_mfma_f32_16x16x32_bf16 v[174:177], v[90:93], v[150:153], v[174:177]
	v_mfma_f32_16x16x32_bf16 v[146:149], v[82:85], v[158:161], v[146:149]
	v_mfma_f32_16x16x32_bf16 v[166:169], v[90:93], v[158:161], v[166:169]
	v_mfma_f32_16x16x32_bf16 v[186:189], v[86:89], v[134:137], v[186:189]
	v_mfma_f32_16x16x32_bf16 v[190:193], v[94:97], v[134:137], v[190:193]
	v_mfma_f32_16x16x32_bf16 v[178:181], v[86:89], v[142:145], v[178:181]
	v_mfma_f32_16x16x32_bf16 v[182:185], v[94:97], v[142:145], v[182:185]
	v_mfma_f32_16x16x32_bf16 v[170:173], v[86:89], v[154:157], v[170:173]
	v_mfma_f32_16x16x32_bf16 v[174:177], v[94:97], v[154:157], v[174:177]
	v_mfma_f32_16x16x32_bf16 v[146:149], v[86:89], v[162:165], v[146:149]
	v_mfma_f32_16x16x32_bf16 v[166:169], v[94:97], v[162:165], v[166:169]
	s_setprio 0
	s_setprio 1
	v_mfma_f32_16x16x32_bf16 v[58:61], v[106:109], v[130:133], v[58:61]
	v_mfma_f32_16x16x32_bf16 v[62:65], v[114:117], v[130:133], v[62:65]
	v_mfma_f32_16x16x32_bf16 v[50:53], v[106:109], v[138:141], v[50:53]
	v_mfma_f32_16x16x32_bf16 v[54:57], v[114:117], v[138:141], v[54:57]
	v_mfma_f32_16x16x32_bf16 v[42:45], v[106:109], v[150:153], v[42:45]
	v_mfma_f32_16x16x32_bf16 v[46:49], v[114:117], v[150:153], v[46:49]
	v_mfma_f32_16x16x32_bf16 v[34:37], v[106:109], v[158:161], v[34:37]
	v_mfma_f32_16x16x32_bf16 v[38:41], v[114:117], v[158:161], v[38:41]
	v_mfma_f32_16x16x32_bf16 v[58:61], v[110:113], v[134:137], v[58:61]
	v_mfma_f32_16x16x32_bf16 v[62:65], v[118:121], v[134:137], v[62:65]
	v_mfma_f32_16x16x32_bf16 v[50:53], v[110:113], v[142:145], v[50:53]
	v_mfma_f32_16x16x32_bf16 v[54:57], v[118:121], v[142:145], v[54:57]
	v_mfma_f32_16x16x32_bf16 v[42:45], v[110:113], v[154:157], v[42:45]
	v_mfma_f32_16x16x32_bf16 v[46:49], v[118:121], v[154:157], v[46:49]
	v_mfma_f32_16x16x32_bf16 v[34:37], v[110:113], v[162:165], v[34:37]
	v_mfma_f32_16x16x32_bf16 v[38:41], v[118:121], v[162:165], v[38:41]
	s_setprio 0
	s_barrier
	s_add_i32 s10, s18, s63
	v_lshl_add_u64 v[194:195], v[194:195], 0, s[30:31]
	s_mov_b32 m0, s10
	ds_read_b128 v[130:133], v244 offset:49152
	ds_read_b128 v[134:137], v244 offset:50176
	ds_read_b128 v[138:141], v244 offset:51200
	ds_read_b128 v[142:145], v244 offset:52224
	ds_read_b128 v[150:153], v244 offset:53248
	ds_read_b128 v[154:157], v244 offset:54272
	ds_read_b128 v[158:161], v244 offset:55296
	ds_read_b128 v[162:165], v244 offset:56320
	global_load_lds_dwordx4 v[194:195], off
	s_add_i32 m0, s10, 0x2000
	s_add_u32 s4, s4, 0x40080
	v_lshl_add_u64 v[194:195], v[196:197], 0, s[30:31]
	s_addc_u32 s5, s5, 0
	s_add_i32 s10, s19, s63
	global_load_lds_dwordx4 v[194:195], off
	v_lshl_add_u64 v[194:195], s[4:5], 0, v[208:209]
	s_mov_b32 m0, s10
	s_nop 0
	global_load_lds_dwordx4 v[194:195], off
	v_lshl_add_u64 v[194:195], s[4:5], 0, v[212:213]
	s_add_i32 m0, s10, 0x2000
	s_nop 0
	global_load_lds_dwordx4 v[194:195], off
	v_lshl_add_u64 v[194:195], v[218:219], 0, s[30:31]
	s_mov_b32 m0, s45
	s_nop 0
	global_load_lds_dwordx4 v[194:195], off
	v_lshl_add_u64 v[194:195], v[220:221], 0, s[30:31]
	s_mov_b32 m0, s46
	s_nop 0
	global_load_lds_dwordx4 v[194:195], off
	s_waitcnt vmcnt(8)
	s_waitcnt lgkmcnt(0)
	s_barrier
	s_setprio 1
	s_waitcnt lgkmcnt(0)
	v_mfma_f32_16x16x32_bf16 v[122:125], v[82:85], v[130:133], v[122:125]
	v_mfma_f32_16x16x32_bf16 v[126:129], v[90:93], v[130:133], v[126:129]
	v_mfma_f32_16x16x32_bf16 v[98:101], v[82:85], v[138:141], v[98:101]
	v_mfma_f32_16x16x32_bf16 v[102:105], v[90:93], v[138:141], v[102:105]
	v_mfma_f32_16x16x32_bf16 v[74:77], v[82:85], v[150:153], v[74:77]
	v_mfma_f32_16x16x32_bf16 v[78:81], v[90:93], v[150:153], v[78:81]
	v_mfma_f32_16x16x32_bf16 v[66:69], v[82:85], v[158:161], v[66:69]
	v_mfma_f32_16x16x32_bf16 v[70:73], v[90:93], v[158:161], v[70:73]
	v_mfma_f32_16x16x32_bf16 v[122:125], v[86:89], v[134:137], v[122:125]
	v_mfma_f32_16x16x32_bf16 v[126:129], v[94:97], v[134:137], v[126:129]
	v_mfma_f32_16x16x32_bf16 v[98:101], v[86:89], v[142:145], v[98:101]
	v_mfma_f32_16x16x32_bf16 v[102:105], v[94:97], v[142:145], v[102:105]
	v_mfma_f32_16x16x32_bf16 v[74:77], v[86:89], v[154:157], v[74:77]
	v_mfma_f32_16x16x32_bf16 v[78:81], v[94:97], v[154:157], v[78:81]
	v_mfma_f32_16x16x32_bf16 v[66:69], v[86:89], v[162:165], v[66:69]
	v_mfma_f32_16x16x32_bf16 v[70:73], v[94:97], v[162:165], v[70:73]
	s_setprio 0
	s_setprio 1
	v_mfma_f32_16x16x32_bf16 v[26:29], v[106:109], v[130:133], v[26:29]
	v_mfma_f32_16x16x32_bf16 v[30:33], v[114:117], v[130:133], v[30:33]
	v_mfma_f32_16x16x32_bf16 v[18:21], v[106:109], v[138:141], v[18:21]
	v_mfma_f32_16x16x32_bf16 v[22:25], v[114:117], v[138:141], v[22:25]
	v_mfma_f32_16x16x32_bf16 v[10:13], v[106:109], v[150:153], v[10:13]
	v_mfma_f32_16x16x32_bf16 v[14:17], v[114:117], v[150:153], v[14:17]
	v_mfma_f32_16x16x32_bf16 v[2:5], v[106:109], v[158:161], v[2:5]
	v_mfma_f32_16x16x32_bf16 v[6:9], v[114:117], v[158:161], v[6:9]
	v_mfma_f32_16x16x32_bf16 v[26:29], v[110:113], v[134:137], v[26:29]
	v_mfma_f32_16x16x32_bf16 v[30:33], v[118:121], v[134:137], v[30:33]
	v_mfma_f32_16x16x32_bf16 v[18:21], v[110:113], v[142:145], v[18:21]
	v_mfma_f32_16x16x32_bf16 v[22:25], v[118:121], v[142:145], v[22:25]
	v_mfma_f32_16x16x32_bf16 v[10:13], v[110:113], v[154:157], v[10:13]
	v_mfma_f32_16x16x32_bf16 v[14:17], v[118:121], v[154:157], v[14:17]
	v_mfma_f32_16x16x32_bf16 v[2:5], v[110:113], v[162:165], v[2:5]
	v_mfma_f32_16x16x32_bf16 v[6:9], v[118:121], v[162:165], v[6:9]
	s_setprio 0
	s_add_i32 s17, s17, 2
	s_add_u32 s8, s8, 0x100
	s_addc_u32 s9, s9, 0
	s_add_u32 s15, s15, 0x100
	s_addc_u32 s16, s16, 0
	s_add_u32 s4, s8, 0xfffc0080
	s_addc_u32 s5, s9, -1
	s_add_i32 s18, 0, 0x10000
	s_cmp_eq_u32 s17, 12
	s_cselect_b32 s11, s1, s5
	s_cselect_b32 s10, s12, s4
	s_cselect_b32 s5, s13, s16
	s_cselect_b32 s4, s14, s15
	s_add_i32 s23, 0, 0x14000
	s_cmp_gt_u32 s17, 13
	s_barrier
	s_cbranch_scc0 .LBB0_478
	v_readlane_b32 s4, v253, 25
	v_readlane_b32 s5, v253, 26
	s_and_b64 vcc, exec, s[4:5]
	s_cbranch_vccz .LBB0_481
	s_barrier

.LBB0_1305:
	v_lshl_add_u64 v[8:9], v[8:9], 0, s[34:35]
	s_add_i32 m0, s14, 0x18000
	s_waitcnt vmcnt(2)
	s_barrier
	global_load_lds_dwordx4 v[8:9], off
	v_lshl_add_u64 v[6:7], v[6:7], 0, s[34:35]
	s_add_i32 m0, s14, 0x1a000
	s_add_i32 s18, s14, 0x8000
	s_add_i32 s19, s14, 0xa000
	global_load_lds_dwordx4 v[6:7], off
	v_lshl_add_u64 v[2:3], v[2:3], 0, s[34:35]
	s_mov_b32 m0, s18
	s_add_u32 s12, s6, 0x80080
	global_load_lds_dwordx4 v[2:3], off
	v_lshl_add_u64 v[2:3], v[4:5], 0, s[34:35]
	s_mov_b32 m0, s19
	s_addc_u32 s13, s7, 0
	global_load_lds_dwordx4 v[2:3], off
	v_lshl_add_u64 v[2:3], s[12:13], 0, v[0:1]
	s_add_i32 m0, s14, 0x1c000
	v_and_b32_e32 v141, 15, v140
	global_load_lds_dwordx4 v[2:3], off
	v_lshl_add_u64 v[2:3], s[12:13], 0, v[94:95]
	s_add_i32 m0, s14, 0x1e000
	s_add_u32 s4, s4, s92
	global_load_lds_dwordx4 v[2:3], off
	s_addc_u32 s12, 0, s93
	s_lshl_b32 s10, s10, 19
	s_and_b32 s10, s10, 0x7c00000
	s_lshl_b32 s11, s11, 19
	s_add_i32 s10, s10, s11
	s_add_u32 s11, s4, s10
	s_addc_u32 s13, s12, 0
	s_add_u32 s20, s76, s11
	s_addc_u32 s21, s77, s13
	v_lshlrev_b32_e32 v2, 14, v10
	v_readlane_b32 s11, v253, 32
	v_and_b32_e32 v2, 0xffff8000, v2
	s_add_u32 s10, s11, s10
	v_readlane_b32 s11, v253, 33
	v_lshl_add_u32 v2, v11, 11, v2
	v_and_b32_e32 v3, 1, v10
	s_addc_u32 s11, s11, 0
	v_lshl_or_b32 v2, v3, 6, v2
	s_add_u32 s10, s10, s4
	v_lshl_add_u32 v2, v12, 1, v2
	v_mov_b32_e32 v3, v1
	s_addc_u32 s11, s11, s12
	v_lshl_add_u64 v[96:97], s[10:11], 0, v[2:3]
	v_lshlrev_b32_e32 v2, 14, v13
	v_and_b32_e32 v2, 0xffff8000, v2
	v_lshl_add_u32 v2, v14, 11, v2
	v_and_b32_e32 v3, 1, v13
	v_lshl_or_b32 v2, v3, 6, v2
	v_lshl_add_u32 v2, v15, 1, v2
	v_mov_b32_e32 v3, v1
	v_readlane_b32 s4, v253, 42
	v_lshl_add_u64 v[138:139], s[10:11], 0, v[2:3]
	s_add_i32 s10, s4, s0
	s_ashr_i32 s11, s10, 31
	s_lshl_b64 s[10:11], s[10:11], 20
	s_add_u32 s4, s92, s10
	s_addc_u32 s10, s93, s11
	v_and_b32_e32 v17, 48, v140
	v_and_b32_e32 v16, 0xfffffc00, v16
	v_lshlrev_b32_e32 v19, 2, v140
	s_add_u32 s4, s4, s5
	v_lshl_or_b32 v17, v141, 6, v17
	v_add_u32_e32 v18, s79, v16
	v_and_b32_e32 v19, 32, v19
	s_waitcnt vmcnt(6)
	s_addc_u32 s5, s10, 0
	v_readlane_b32 s10, v253, 34
	v_bitop3_b32 v18, v17, v18, v19 bitop3:0xde
	v_add_u32_e32 v16, s82, v16
	s_add_u32 s22, s10, s4
	v_readlane_b32 s4, v253, 35
	v_mov_b32_e32 v2, 0
	v_bitop3_b32 v142, v17, v16, v19 bitop3:0xde
	s_addc_u32 s23, s4, s5
	s_mov_b32 s24, -2
	s_mov_b64 s[10:11], 0
	v_add_u32_e32 v143, 0, v18
	v_mov_b32_e32 v3, v2
	v_mov_b32_e32 v4, v2
	v_mov_b32_e32 v5, v2
	v_mov_b32_e32 v6, v2
	v_mov_b32_e32 v7, v2
	v_mov_b32_e32 v8, v2
	v_mov_b32_e32 v9, v2
	v_mov_b32_e32 v10, v2
	v_mov_b32_e32 v11, v2
	v_mov_b32_e32 v12, v2
	v_mov_b32_e32 v13, v2
	v_mov_b32_e32 v14, v2
	v_mov_b32_e32 v15, v2
	v_mov_b32_e32 v16, v2
	v_mov_b32_e32 v17, v2
	v_mov_b32_e32 v18, v2
	v_mov_b32_e32 v19, v2
	v_mov_b32_e32 v20, v2
	v_mov_b32_e32 v21, v2
	v_mov_b32_e32 v22, v2
	v_mov_b32_e32 v23, v2
	v_mov_b32_e32 v24, v2
	v_mov_b32_e32 v25, v2
	v_mov_b32_e32 v26, v2
	v_mov_b32_e32 v27, v2
	v_mov_b32_e32 v28, v2
	v_mov_b32_e32 v29, v2
	v_mov_b32_e32 v30, v2
	v_mov_b32_e32 v31, v2
	v_mov_b32_e32 v32, v2
	v_mov_b32_e32 v33, v2
	v_mov_b32_e32 v66, v2
	v_mov_b32_e32 v67, v2
	v_mov_b32_e32 v68, v2
	v_mov_b32_e32 v69, v2
	v_mov_b32_e32 v70, v2
	v_mov_b32_e32 v71, v2
	v_mov_b32_e32 v72, v2
	v_mov_b32_e32 v73, v2
	v_mov_b32_e32 v74, v2
	v_mov_b32_e32 v75, v2
	v_mov_b32_e32 v76, v2
	v_mov_b32_e32 v77, v2
	v_mov_b32_e32 v78, v2
	v_mov_b32_e32 v79, v2
	v_mov_b32_e32 v80, v2
	v_mov_b32_e32 v81, v2
	v_mov_b32_e32 v82, v2
	v_mov_b32_e32 v83, v2
	v_mov_b32_e32 v84, v2
	v_mov_b32_e32 v85, v2
	v_mov_b32_e32 v86, v2
	v_mov_b32_e32 v87, v2
	v_mov_b32_e32 v88, v2
	v_mov_b32_e32 v89, v2
	v_mov_b32_e32 v98, v2
	v_mov_b32_e32 v99, v2
	v_mov_b32_e32 v100, v2
	v_mov_b32_e32 v101, v2
	v_mov_b32_e32 v102, v2
	v_mov_b32_e32 v103, v2
	v_mov_b32_e32 v104, v2
	v_mov_b32_e32 v105, v2
	v_mov_b32_e32 v34, v2
	v_mov_b32_e32 v35, v2
	v_mov_b32_e32 v36, v2
	v_mov_b32_e32 v37, v2
	v_mov_b32_e32 v38, v2
	v_mov_b32_e32 v39, v2
	v_mov_b32_e32 v40, v2
	v_mov_b32_e32 v41, v2
	v_mov_b32_e32 v42, v2
	v_mov_b32_e32 v43, v2
	v_mov_b32_e32 v44, v2
	v_mov_b32_e32 v45, v2
	v_mov_b32_e32 v46, v2
	v_mov_b32_e32 v47, v2
	v_mov_b32_e32 v48, v2
	v_mov_b32_e32 v49, v2
	v_mov_b32_e32 v50, v2
	v_mov_b32_e32 v51, v2
	v_mov_b32_e32 v52, v2
	v_mov_b32_e32 v53, v2
	v_mov_b32_e32 v54, v2
	v_mov_b32_e32 v55, v2
	v_mov_b32_e32 v56, v2
	v_mov_b32_e32 v57, v2
	v_mov_b32_e32 v58, v2
	v_mov_b32_e32 v59, v2
	v_mov_b32_e32 v60, v2
	v_mov_b32_e32 v61, v2
	v_mov_b32_e32 v62, v2
	v_mov_b32_e32 v63, v2
	v_mov_b32_e32 v64, v2
	v_mov_b32_e32 v65, v2
	v_mov_b32_e32 v106, v2
	v_mov_b32_e32 v107, v2
	v_mov_b32_e32 v108, v2
	v_mov_b32_e32 v109, v2
	v_mov_b32_e32 v110, v2
	v_mov_b32_e32 v111, v2
	v_mov_b32_e32 v112, v2
	v_mov_b32_e32 v113, v2
	v_mov_b32_e32 v114, v2
	v_mov_b32_e32 v115, v2
	v_mov_b32_e32 v116, v2
	v_mov_b32_e32 v117, v2
	v_mov_b32_e32 v118, v2
	v_mov_b32_e32 v119, v2
	v_mov_b32_e32 v120, v2
	v_mov_b32_e32 v121, v2
	v_mov_b32_e32 v122, v2
	v_mov_b32_e32 v123, v2
	v_mov_b32_e32 v124, v2
	v_mov_b32_e32 v125, v2
	v_mov_b32_e32 v126, v2
	v_mov_b32_e32 v127, v2
	v_mov_b32_e32 v128, v2
	v_mov_b32_e32 v129, v2
	v_mov_b32_e32 v130, v2
	v_mov_b32_e32 v131, v2
	v_mov_b32_e32 v132, v2
	v_mov_b32_e32 v133, v2
	v_mov_b32_e32 v134, v2
	v_mov_b32_e32 v135, v2
	v_mov_b32_e32 v136, v2
	v_mov_b32_e32 v137, v2
	s_barrier
	s_add_u32 s4, s20, s10
	s_addc_u32 s5, s21, s11
	s_add_u32 s4, s4, 0x100
	s_addc_u32 s5, s5, 0
	s_add_u32 s25, s22, s10
	s_addc_u32 s26, s23, s11
	s_add_i32 s27, 0, 0x10000
	s_cmpk_eq_i32 s10, 0xf00
	s_cselect_b32 s13, s9, s5
	s_cselect_b32 s12, s8, s4
	s_cselect_b32 s5, s7, s26
	s_cselect_b32 s4, s6, s25
	s_add_i32 s25, 0, 0x14000
.LBB0_1306:
	v_add_u32_e32 v156, s27, v142
	v_add_u32_e32 v172, s25, v142
	ds_read_b128 v[144:147], v156
	ds_read_b128 v[148:151], v156 offset:1024
	ds_read_b128 v[152:155], v156 offset:2048
	ds_read_b128 v[156:159], v156 offset:3072
	ds_read_b128 v[160:163], v172
	ds_read_b128 v[164:167], v172 offset:1024
	ds_read_b128 v[168:171], v172 offset:2048
	ds_read_b128 v[172:175], v172 offset:3072
	v_lshl_add_u64 v[196:197], v[96:97], 0, s[10:11]
	s_add_i32 m0, s14, 0xc000
	ds_read_b128 v[176:179], v143
	ds_read_b128 v[180:183], v143 offset:1024
	ds_read_b128 v[184:187], v143 offset:2048
	ds_read_b128 v[188:191], v143 offset:3072
	ds_read_b128 v[192:195], v143 offset:4096
	ds_read_b128 v[206:209], v143 offset:5120
	ds_read_b128 v[210:213], v143 offset:6144
	ds_read_b128 v[214:217], v143 offset:7168
	global_load_lds_dwordx4 v[196:197], off
	v_lshl_add_u64 v[196:197], v[138:139], 0, s[10:11]
	s_add_i32 m0, s14, 0xe000
	s_nop 0
	global_load_lds_dwordx4 v[196:197], off
	s_waitcnt vmcnt(8)
	s_waitcnt lgkmcnt(0)
	s_barrier
	s_setprio 1
	s_waitcnt lgkmcnt(0)
	v_mfma_f32_16x16x32_bf16 v[134:137], v[144:147], v[176:179], v[134:137]
	v_mfma_f32_16x16x32_bf16 v[130:133], v[152:155], v[176:179], v[130:133]
	v_mfma_f32_16x16x32_bf16 v[126:129], v[144:147], v[184:187], v[126:129]
	v_mfma_f32_16x16x32_bf16 v[122:125], v[152:155], v[184:187], v[122:125]
	v_mfma_f32_16x16x32_bf16 v[118:121], v[144:147], v[192:195], v[118:121]
	v_mfma_f32_16x16x32_bf16 v[114:117], v[152:155], v[192:195], v[114:117]
	v_mfma_f32_16x16x32_bf16 v[110:113], v[144:147], v[210:213], v[110:113]
	v_mfma_f32_16x16x32_bf16 v[106:109], v[152:155], v[210:213], v[106:109]
	v_mfma_f32_16x16x32_bf16 v[134:137], v[148:151], v[180:183], v[134:137]
	v_mfma_f32_16x16x32_bf16 v[130:133], v[156:159], v[180:183], v[130:133]
	v_mfma_f32_16x16x32_bf16 v[126:129], v[148:151], v[188:191], v[126:129]
	v_mfma_f32_16x16x32_bf16 v[122:125], v[156:159], v[188:191], v[122:125]
	v_mfma_f32_16x16x32_bf16 v[118:121], v[148:151], v[206:209], v[118:121]
	v_mfma_f32_16x16x32_bf16 v[114:117], v[156:159], v[206:209], v[114:117]
	v_mfma_f32_16x16x32_bf16 v[110:113], v[148:151], v[214:217], v[110:113]
	v_mfma_f32_16x16x32_bf16 v[106:109], v[156:159], v[214:217], v[106:109]
	s_setprio 0
	s_setprio 1
	v_mfma_f32_16x16x32_bf16 v[62:65], v[160:163], v[176:179], v[62:65]
	v_mfma_f32_16x16x32_bf16 v[58:61], v[168:171], v[176:179], v[58:61]
	v_mfma_f32_16x16x32_bf16 v[54:57], v[160:163], v[184:187], v[54:57]
	v_mfma_f32_16x16x32_bf16 v[50:53], v[168:171], v[184:187], v[50:53]
	v_mfma_f32_16x16x32_bf16 v[46:49], v[160:163], v[192:195], v[46:49]
	v_mfma_f32_16x16x32_bf16 v[42:45], v[168:171], v[192:195], v[42:45]
	v_mfma_f32_16x16x32_bf16 v[38:41], v[160:163], v[210:213], v[38:41]
	v_mfma_f32_16x16x32_bf16 v[34:37], v[168:171], v[210:213], v[34:37]
	v_mfma_f32_16x16x32_bf16 v[62:65], v[164:167], v[180:183], v[62:65]
	v_mfma_f32_16x16x32_bf16 v[58:61], v[172:175], v[180:183], v[58:61]
	v_mfma_f32_16x16x32_bf16 v[54:57], v[164:167], v[188:191], v[54:57]
	v_mfma_f32_16x16x32_bf16 v[50:53], v[172:175], v[188:191], v[50:53]
	v_mfma_f32_16x16x32_bf16 v[46:49], v[164:167], v[206:209], v[46:49]
	v_mfma_f32_16x16x32_bf16 v[42:45], v[172:175], v[206:209], v[42:45]
	v_mfma_f32_16x16x32_bf16 v[38:41], v[164:167], v[214:217], v[38:41]
	v_mfma_f32_16x16x32_bf16 v[34:37], v[172:175], v[214:217], v[34:37]
	s_setprio 0
	s_barrier
	s_add_i32 s26, s27, s63
	v_lshl_add_u64 v[196:197], s[4:5], 0, v[0:1]
	s_mov_b32 m0, s26
	ds_read_b128 v[176:179], v143 offset:16384
	ds_read_b128 v[180:183], v143 offset:17408
	ds_read_b128 v[184:187], v143 offset:18432
	ds_read_b128 v[188:191], v143 offset:19456
	ds_read_b128 v[192:195], v143 offset:20480
	ds_read_b128 v[206:209], v143 offset:21504
	ds_read_b128 v[210:213], v143 offset:22528
	ds_read_b128 v[214:217], v143 offset:23552
	global_load_lds_dwordx4 v[196:197], off
	s_add_i32 m0, s26, 0x2000
	s_add_u32 s26, s4, 0x80000
	v_lshl_add_u64 v[202:203], s[4:5], 0, v[94:95]
	s_addc_u32 s27, s5, 0
	s_add_i32 s25, s25, s63
	global_load_lds_dwordx4 v[202:203], off
	v_lshl_add_u64 v[218:219], s[26:27], 0, v[0:1]
	s_mov_b32 m0, s25
	v_lshl_add_u64 v[220:221], s[12:13], 0, v[92:93]
	global_load_lds_dwordx4 v[218:219], off
	v_lshl_add_u64 v[218:219], s[26:27], 0, v[94:95]
	s_add_i32 m0, s25, 0x2000
	s_nop 0
	global_load_lds_dwordx4 v[218:219], off
	v_lshl_add_u64 v[218:219], s[12:13], 0, v[90:91]
	s_mov_b32 m0, s14
	s_nop 0
	global_load_lds_dwordx4 v[218:219], off
	s_mov_b32 m0, s15
	s_nop 0
	global_load_lds_dwordx4 v[220:221], off
	s_waitcnt vmcnt(8)
	s_waitcnt lgkmcnt(0)
	s_barrier
	s_setprio 1
	s_waitcnt lgkmcnt(0)
	v_mfma_f32_16x16x32_bf16 v[102:105], v[144:147], v[176:179], v[102:105]
	v_mfma_f32_16x16x32_bf16 v[98:101], v[152:155], v[176:179], v[98:101]
	v_mfma_f32_16x16x32_bf16 v[86:89], v[144:147], v[184:187], v[86:89]
	v_mfma_f32_16x16x32_bf16 v[82:85], v[152:155], v[184:187], v[82:85]
	v_mfma_f32_16x16x32_bf16 v[78:81], v[144:147], v[192:195], v[78:81]
	v_mfma_f32_16x16x32_bf16 v[74:77], v[152:155], v[192:195], v[74:77]
	v_mfma_f32_16x16x32_bf16 v[70:73], v[144:147], v[210:213], v[70:73]
	v_mfma_f32_16x16x32_bf16 v[66:69], v[152:155], v[210:213], v[66:69]
	v_mfma_f32_16x16x32_bf16 v[102:105], v[148:151], v[180:183], v[102:105]
	v_mfma_f32_16x16x32_bf16 v[98:101], v[156:159], v[180:183], v[98:101]
	v_mfma_f32_16x16x32_bf16 v[86:89], v[148:151], v[188:191], v[86:89]
	v_mfma_f32_16x16x32_bf16 v[82:85], v[156:159], v[188:191], v[82:85]
	v_mfma_f32_16x16x32_bf16 v[78:81], v[148:151], v[206:209], v[78:81]
	v_mfma_f32_16x16x32_bf16 v[74:77], v[156:159], v[206:209], v[74:77]
	v_mfma_f32_16x16x32_bf16 v[70:73], v[148:151], v[214:217], v[70:73]
	v_mfma_f32_16x16x32_bf16 v[66:69], v[156:159], v[214:217], v[66:69]
	s_setprio 0
	s_setprio 1
	v_mfma_f32_16x16x32_bf16 v[30:33], v[160:163], v[176:179], v[30:33]
	v_mfma_f32_16x16x32_bf16 v[26:29], v[168:171], v[176:179], v[26:29]
	v_mfma_f32_16x16x32_bf16 v[22:25], v[160:163], v[184:187], v[22:25]
	v_mfma_f32_16x16x32_bf16 v[18:21], v[168:171], v[184:187], v[18:21]
	v_mfma_f32_16x16x32_bf16 v[14:17], v[160:163], v[192:195], v[14:17]
	v_mfma_f32_16x16x32_bf16 v[10:13], v[168:171], v[192:195], v[10:13]
	v_mfma_f32_16x16x32_bf16 v[6:9], v[160:163], v[210:213], v[6:9]
	v_mfma_f32_16x16x32_bf16 v[2:5], v[168:171], v[210:213], v[2:5]
	v_mfma_f32_16x16x32_bf16 v[30:33], v[164:167], v[180:183], v[30:33]
	v_mfma_f32_16x16x32_bf16 v[26:29], v[172:175], v[180:183], v[26:29]
	v_mfma_f32_16x16x32_bf16 v[22:25], v[164:167], v[188:191], v[22:25]
	v_mfma_f32_16x16x32_bf16 v[18:21], v[172:175], v[188:191], v[18:21]
	v_mfma_f32_16x16x32_bf16 v[14:17], v[164:167], v[206:209], v[14:17]
	v_mfma_f32_16x16x32_bf16 v[10:13], v[172:175], v[206:209], v[10:13]
	v_mfma_f32_16x16x32_bf16 v[6:9], v[164:167], v[214:217], v[6:9]
	v_mfma_f32_16x16x32_bf16 v[2:5], v[172:175], v[214:217], v[2:5]
	s_setprio 0
	s_barrier
	s_add_i32 s25, 0, 0x18000
	s_add_i32 s26, 0, 0x1c000
	v_add_u32_e32 v156, s25, v142
	v_add_u32_e32 v172, s26, v142
	ds_read_b128 v[144:147], v156
	ds_read_b128 v[148:151], v156 offset:1024
	ds_read_b128 v[152:155], v156 offset:2048
	ds_read_b128 v[156:159], v156 offset:3072
	ds_read_b128 v[160:163], v172
	ds_read_b128 v[164:167], v172 offset:1024
	ds_read_b128 v[168:171], v172 offset:2048
	ds_read_b128 v[172:175], v172 offset:3072
	s_add_u32 s12, s12, 0x40000
	s_addc_u32 s13, s13, 0
	s_mov_b32 m0, s16
	v_lshl_add_u64 v[222:223], s[12:13], 0, v[90:91]
	ds_read_b128 v[176:179], v143 offset:32768
	ds_read_b128 v[180:183], v143 offset:33792
	ds_read_b128 v[184:187], v143 offset:34816
	ds_read_b128 v[188:191], v143 offset:35840
	ds_read_b128 v[192:195], v143 offset:36864
	ds_read_b128 v[206:209], v143 offset:37888
	ds_read_b128 v[210:213], v143 offset:38912
	ds_read_b128 v[214:217], v143 offset:39936
	global_load_lds_dwordx4 v[222:223], off
	v_lshl_add_u64 v[222:223], s[12:13], 0, v[92:93]
	s_mov_b32 m0, s17
	s_nop 0
	global_load_lds_dwordx4 v[222:223], off
	s_waitcnt vmcnt(8)
	s_waitcnt lgkmcnt(0)
	s_barrier
	s_setprio 1
	s_waitcnt lgkmcnt(0)
	v_mfma_f32_16x16x32_bf16 v[134:137], v[144:147], v[176:179], v[134:137]
	v_mfma_f32_16x16x32_bf16 v[130:133], v[152:155], v[176:179], v[130:133]
	v_mfma_f32_16x16x32_bf16 v[126:129], v[144:147], v[184:187], v[126:129]
	v_mfma_f32_16x16x32_bf16 v[122:125], v[152:155], v[184:187], v[122:125]
	v_mfma_f32_16x16x32_bf16 v[118:121], v[144:147], v[192:195], v[118:121]
	v_mfma_f32_16x16x32_bf16 v[114:117], v[152:155], v[192:195], v[114:117]
	v_mfma_f32_16x16x32_bf16 v[110:113], v[144:147], v[210:213], v[110:113]
	v_mfma_f32_16x16x32_bf16 v[106:109], v[152:155], v[210:213], v[106:109]
	v_mfma_f32_16x16x32_bf16 v[134:137], v[148:151], v[180:183], v[134:137]
	v_mfma_f32_16x16x32_bf16 v[130:133], v[156:159], v[180:183], v[130:133]
	v_mfma_f32_16x16x32_bf16 v[126:129], v[148:151], v[188:191], v[126:129]
	v_mfma_f32_16x16x32_bf16 v[122:125], v[156:159], v[188:191], v[122:125]
	v_mfma_f32_16x16x32_bf16 v[118:121], v[148:151], v[206:209], v[118:121]
	v_mfma_f32_16x16x32_bf16 v[114:117], v[156:159], v[206:209], v[114:117]
	v_mfma_f32_16x16x32_bf16 v[110:113], v[148:151], v[214:217], v[110:113]
	v_mfma_f32_16x16x32_bf16 v[106:109], v[156:159], v[214:217], v[106:109]
	s_setprio 0
	s_setprio 1
	v_mfma_f32_16x16x32_bf16 v[62:65], v[160:163], v[176:179], v[62:65]
	v_mfma_f32_16x16x32_bf16 v[58:61], v[168:171], v[176:179], v[58:61]
	v_mfma_f32_16x16x32_bf16 v[54:57], v[160:163], v[184:187], v[54:57]
	v_mfma_f32_16x16x32_bf16 v[50:53], v[168:171], v[184:187], v[50:53]
	v_mfma_f32_16x16x32_bf16 v[46:49], v[160:163], v[192:195], v[46:49]
	v_mfma_f32_16x16x32_bf16 v[42:45], v[168:171], v[192:195], v[42:45]
	v_mfma_f32_16x16x32_bf16 v[38:41], v[160:163], v[210:213], v[38:41]
	v_mfma_f32_16x16x32_bf16 v[34:37], v[168:171], v[210:213], v[34:37]
	v_mfma_f32_16x16x32_bf16 v[62:65], v[164:167], v[180:183], v[62:65]
	v_mfma_f32_16x16x32_bf16 v[58:61], v[172:175], v[180:183], v[58:61]
	v_mfma_f32_16x16x32_bf16 v[54:57], v[164:167], v[188:191], v[54:57]
	v_mfma_f32_16x16x32_bf16 v[50:53], v[172:175], v[188:191], v[50:53]
	v_mfma_f32_16x16x32_bf16 v[46:49], v[164:167], v[206:209], v[46:49]
	v_mfma_f32_16x16x32_bf16 v[42:45], v[172:175], v[206:209], v[42:45]
	v_mfma_f32_16x16x32_bf16 v[38:41], v[164:167], v[214:217], v[38:41]
	v_mfma_f32_16x16x32_bf16 v[34:37], v[172:175], v[214:217], v[34:37]
	s_setprio 0
	s_barrier
	s_add_i32 s12, s25, s63
	v_lshl_add_u64 v[196:197], v[196:197], 0, s[34:35]
	s_mov_b32 m0, s12
	ds_read_b128 v[176:179], v143 offset:49152
	ds_read_b128 v[180:183], v143 offset:50176
	ds_read_b128 v[184:187], v143 offset:51200
	ds_read_b128 v[188:191], v143 offset:52224
	ds_read_b128 v[192:195], v143 offset:53248
	ds_read_b128 v[206:209], v143 offset:54272
	ds_read_b128 v[210:213], v143 offset:55296
	ds_read_b128 v[214:217], v143 offset:56320
	global_load_lds_dwordx4 v[196:197], off
	s_add_i32 m0, s12, 0x2000
	s_add_u32 s4, s4, 0x80080
	v_lshl_add_u64 v[196:197], v[202:203], 0, s[34:35]
	s_addc_u32 s5, s5, 0
	s_add_i32 s12, s26, s63
	global_load_lds_dwordx4 v[196:197], off
	v_lshl_add_u64 v[196:197], s[4:5], 0, v[0:1]
	s_mov_b32 m0, s12
	s_nop 0
	global_load_lds_dwordx4 v[196:197], off
	v_lshl_add_u64 v[196:197], s[4:5], 0, v[94:95]
	s_add_i32 m0, s12, 0x2000
	s_nop 0
	global_load_lds_dwordx4 v[196:197], off
	v_lshl_add_u64 v[196:197], v[218:219], 0, s[34:35]
	s_mov_b32 m0, s18
	s_nop 0
	global_load_lds_dwordx4 v[196:197], off
	v_lshl_add_u64 v[196:197], v[220:221], 0, s[34:35]
	s_mov_b32 m0, s19
	s_nop 0
	global_load_lds_dwordx4 v[196:197], off
	s_waitcnt vmcnt(8)
	s_waitcnt lgkmcnt(0)
	s_barrier
	s_setprio 1
	s_waitcnt lgkmcnt(0)
	v_mfma_f32_16x16x32_bf16 v[102:105], v[144:147], v[176:179], v[102:105]
	v_mfma_f32_16x16x32_bf16 v[98:101], v[152:155], v[176:179], v[98:101]
	v_mfma_f32_16x16x32_bf16 v[86:89], v[144:147], v[184:187], v[86:89]
	v_mfma_f32_16x16x32_bf16 v[82:85], v[152:155], v[184:187], v[82:85]
	v_mfma_f32_16x16x32_bf16 v[78:81], v[144:147], v[192:195], v[78:81]
	v_mfma_f32_16x16x32_bf16 v[74:77], v[152:155], v[192:195], v[74:77]
	v_mfma_f32_16x16x32_bf16 v[70:73], v[144:147], v[210:213], v[70:73]
	v_mfma_f32_16x16x32_bf16 v[66:69], v[152:155], v[210:213], v[66:69]
	v_mfma_f32_16x16x32_bf16 v[102:105], v[148:151], v[180:183], v[102:105]
	v_mfma_f32_16x16x32_bf16 v[98:101], v[156:159], v[180:183], v[98:101]
	v_mfma_f32_16x16x32_bf16 v[86:89], v[148:151], v[188:191], v[86:89]
	v_mfma_f32_16x16x32_bf16 v[82:85], v[156:159], v[188:191], v[82:85]
	v_mfma_f32_16x16x32_bf16 v[78:81], v[148:151], v[206:209], v[78:81]
	v_mfma_f32_16x16x32_bf16 v[74:77], v[156:159], v[206:209], v[74:77]
	v_mfma_f32_16x16x32_bf16 v[70:73], v[148:151], v[214:217], v[70:73]
	v_mfma_f32_16x16x32_bf16 v[66:69], v[156:159], v[214:217], v[66:69]
	s_setprio 0
	s_setprio 1
	v_mfma_f32_16x16x32_bf16 v[30:33], v[160:163], v[176:179], v[30:33]
	v_mfma_f32_16x16x32_bf16 v[26:29], v[168:171], v[176:179], v[26:29]
	v_mfma_f32_16x16x32_bf16 v[22:25], v[160:163], v[184:187], v[22:25]
	v_mfma_f32_16x16x32_bf16 v[18:21], v[168:171], v[184:187], v[18:21]
	v_mfma_f32_16x16x32_bf16 v[14:17], v[160:163], v[192:195], v[14:17]
	v_mfma_f32_16x16x32_bf16 v[10:13], v[168:171], v[192:195], v[10:13]
	v_mfma_f32_16x16x32_bf16 v[6:9], v[160:163], v[210:213], v[6:9]
	v_mfma_f32_16x16x32_bf16 v[2:5], v[168:171], v[210:213], v[2:5]
	v_mfma_f32_16x16x32_bf16 v[30:33], v[164:167], v[180:183], v[30:33]
	v_mfma_f32_16x16x32_bf16 v[26:29], v[172:175], v[180:183], v[26:29]
	v_mfma_f32_16x16x32_bf16 v[22:25], v[164:167], v[188:191], v[22:25]
	v_mfma_f32_16x16x32_bf16 v[18:21], v[172:175], v[188:191], v[18:21]
	v_mfma_f32_16x16x32_bf16 v[14:17], v[164:167], v[206:209], v[14:17]
	v_mfma_f32_16x16x32_bf16 v[10:13], v[172:175], v[206:209], v[10:13]
	v_mfma_f32_16x16x32_bf16 v[6:9], v[164:167], v[214:217], v[6:9]
	v_mfma_f32_16x16x32_bf16 v[2:5], v[172:175], v[214:217], v[2:5]
	s_setprio 0
	s_add_i32 s24, s24, 2
	s_add_u32 s10, s10, 0x100
	s_addc_u32 s11, s11, 0
	s_add_u32 s4, s20, s10
	s_addc_u32 s5, s21, s11
	s_add_u32 s4, s4, 0x100
	s_addc_u32 s5, s5, 0
	s_add_u32 s25, s22, s10
	s_addc_u32 s26, s23, s11
	s_add_i32 s27, 0, 0x10000
	s_cmpk_eq_i32 s10, 0xf00
	s_cselect_b32 s13, s9, s5
	s_cselect_b32 s12, s8, s4
	s_cselect_b32 s5, s7, s26
	s_cselect_b32 s4, s6, s25
	s_add_i32 s25, 0, 0x14000
	s_cmp_gt_u32 s24, 29
	s_barrier
	s_cbranch_scc0 .LBB0_1306
	v_readlane_b32 s4, v253, 25
	v_readlane_b32 s5, v253, 26
	s_and_b64 vcc, exec, s[4:5]
	s_cbranch_vccz .LBB0_1309
	s_barrier

.LBB0_1712:
	s_ashr_i32 s3, s2, 31
	s_lshl_b64 s[8:9], s[2:3], 19
	v_readlane_b32 s10, v254, 43
	v_readlane_b32 s11, v254, 44
	s_add_u32 s8, s10, s8
	s_addc_u32 s9, s11, s9
	s_and_b64 s[10:11], s[6:7], exec
	s_cselect_b32 s3, s9, s15
	s_cselect_b32 s28, s8, s14
	s_ashr_i32 s1, s0, 31
	s_lshl_b64 s[10:11], s[0:1], 19
	s_add_u32 s10, s19, s10
	s_addc_u32 s11, s20, s11
	s_and_b64 s[16:17], s[6:7], exec
	s_cselect_b32 s1, s11, s5
	s_cselect_b32 s29, s10, s4
	s_add_u32 s14, s14, 0x40080
	s_addc_u32 s15, s15, 0
	s_add_u32 s30, s4, 0x100
	v_mov_b32_e32 v2, 0
	s_addc_u32 s34, s5, 0
	s_mov_b32 s35, -2
	v_mov_b32_e32 v3, v2
	v_mov_b32_e32 v4, v2
	v_mov_b32_e32 v5, v2
	v_mov_b32_e32 v34, v2
	v_mov_b32_e32 v35, v2
	v_mov_b32_e32 v36, v2
	v_mov_b32_e32 v37, v2
	v_mov_b32_e32 v6, v2
	v_mov_b32_e32 v7, v2
	v_mov_b32_e32 v8, v2
	v_mov_b32_e32 v9, v2
	v_mov_b32_e32 v38, v2
	v_mov_b32_e32 v39, v2
	v_mov_b32_e32 v40, v2
	v_mov_b32_e32 v41, v2
	v_mov_b32_e32 v10, v2
	v_mov_b32_e32 v11, v2
	v_mov_b32_e32 v12, v2
	v_mov_b32_e32 v13, v2
	v_mov_b32_e32 v42, v2
	v_mov_b32_e32 v43, v2
	v_mov_b32_e32 v44, v2
	v_mov_b32_e32 v45, v2
	v_mov_b32_e32 v14, v2
	v_mov_b32_e32 v15, v2
	v_mov_b32_e32 v16, v2
	v_mov_b32_e32 v17, v2
	v_mov_b32_e32 v46, v2
	v_mov_b32_e32 v47, v2
	v_mov_b32_e32 v48, v2
	v_mov_b32_e32 v49, v2
	v_mov_b32_e32 v66, v2
	v_mov_b32_e32 v67, v2
	v_mov_b32_e32 v68, v2
	v_mov_b32_e32 v69, v2
	v_mov_b32_e32 v98, v2
	v_mov_b32_e32 v99, v2
	v_mov_b32_e32 v100, v2
	v_mov_b32_e32 v101, v2
	v_mov_b32_e32 v70, v2
	v_mov_b32_e32 v71, v2
	v_mov_b32_e32 v72, v2
	v_mov_b32_e32 v73, v2
	v_mov_b32_e32 v102, v2
	v_mov_b32_e32 v103, v2
	v_mov_b32_e32 v104, v2
	v_mov_b32_e32 v105, v2
	v_mov_b32_e32 v74, v2
	v_mov_b32_e32 v75, v2
	v_mov_b32_e32 v76, v2
	v_mov_b32_e32 v77, v2
	v_mov_b32_e32 v106, v2
	v_mov_b32_e32 v107, v2
	v_mov_b32_e32 v108, v2
	v_mov_b32_e32 v109, v2
	v_mov_b32_e32 v78, v2
	v_mov_b32_e32 v79, v2
	v_mov_b32_e32 v80, v2
	v_mov_b32_e32 v81, v2
	v_mov_b32_e32 v110, v2
	v_mov_b32_e32 v111, v2
	v_mov_b32_e32 v112, v2
	v_mov_b32_e32 v113, v2
	v_mov_b32_e32 v18, v2
	v_mov_b32_e32 v19, v2
	v_mov_b32_e32 v20, v2
	v_mov_b32_e32 v21, v2
	v_mov_b32_e32 v50, v2
	v_mov_b32_e32 v51, v2
	v_mov_b32_e32 v52, v2
	v_mov_b32_e32 v53, v2
	v_mov_b32_e32 v22, v2
	v_mov_b32_e32 v23, v2
	v_mov_b32_e32 v24, v2
	v_mov_b32_e32 v25, v2
	v_mov_b32_e32 v54, v2
	v_mov_b32_e32 v55, v2
	v_mov_b32_e32 v56, v2
	v_mov_b32_e32 v57, v2
	v_mov_b32_e32 v26, v2
	v_mov_b32_e32 v27, v2
	v_mov_b32_e32 v28, v2
	v_mov_b32_e32 v29, v2
	v_mov_b32_e32 v58, v2
	v_mov_b32_e32 v59, v2
	v_mov_b32_e32 v60, v2
	v_mov_b32_e32 v61, v2
	v_mov_b32_e32 v30, v2
	v_mov_b32_e32 v31, v2
	v_mov_b32_e32 v32, v2
	v_mov_b32_e32 v33, v2
	v_mov_b32_e32 v62, v2
	v_mov_b32_e32 v63, v2
	v_mov_b32_e32 v64, v2
	v_mov_b32_e32 v65, v2
	v_mov_b32_e32 v82, v2
	v_mov_b32_e32 v83, v2
	v_mov_b32_e32 v84, v2
	v_mov_b32_e32 v85, v2
	v_mov_b32_e32 v114, v2
	v_mov_b32_e32 v115, v2
	v_mov_b32_e32 v116, v2
	v_mov_b32_e32 v117, v2
	v_mov_b32_e32 v86, v2
	v_mov_b32_e32 v87, v2
	v_mov_b32_e32 v88, v2
	v_mov_b32_e32 v89, v2
	v_mov_b32_e32 v118, v2
	v_mov_b32_e32 v119, v2
	v_mov_b32_e32 v120, v2
	v_mov_b32_e32 v121, v2
	v_mov_b32_e32 v90, v2
	v_mov_b32_e32 v91, v2
	v_mov_b32_e32 v92, v2
	v_mov_b32_e32 v93, v2
	v_mov_b32_e32 v122, v2
	v_mov_b32_e32 v123, v2
	v_mov_b32_e32 v124, v2
	v_mov_b32_e32 v125, v2
	v_mov_b32_e32 v94, v2
	v_mov_b32_e32 v95, v2
	v_mov_b32_e32 v96, v2
	v_mov_b32_e32 v97, v2
	v_mov_b32_e32 v126, v2
	v_mov_b32_e32 v127, v2
	v_mov_b32_e32 v128, v2
	v_mov_b32_e32 v129, v2
	s_add_u32 s4, s14, 0xfffc0080
	s_addc_u32 s5, s15, -1
	s_add_i32 s36, 0, 0x10000
	s_cmp_eq_u32 s35, 12
	s_cselect_b32 s17, s3, s5
	s_cselect_b32 s16, s28, s4
	s_cselect_b32 s5, s1, s34
	s_cselect_b32 s4, s29, s30
	s_add_i32 s42, 0, 0x14000
.LBB0_1713:
	v_add_u32_e32 v148, s36, v158
	v_add_u32_e32 v168, s42, v158
	ds_read_b128 v[136:139], v148
	ds_read_b128 v[140:143], v148 offset:1024
	ds_read_b128 v[144:147], v148 offset:2048
	ds_read_b128 v[148:151], v148 offset:3072
	ds_read_b128 v[152:155], v168
	ds_read_b128 v[160:163], v168 offset:1024
	ds_read_b128 v[164:167], v168 offset:2048
	ds_read_b128 v[168:171], v168 offset:3072
	v_lshl_add_u64 v[196:197], s[14:15], 0, v[132:133]
	s_add_i32 m0, s13, 0xc000
	ds_read_b128 v[172:175], v159
	ds_read_b128 v[176:179], v159 offset:1024
	ds_read_b128 v[180:183], v159 offset:2048
	ds_read_b128 v[184:187], v159 offset:3072
	ds_read_b128 v[188:191], v159 offset:4096
	ds_read_b128 v[192:195], v159 offset:5120
	ds_read_b128 v[206:209], v159 offset:6144
	ds_read_b128 v[210:213], v159 offset:7168
	global_load_lds_dwordx4 v[196:197], off
	v_lshl_add_u64 v[196:197], s[14:15], 0, v[134:135]
	s_add_i32 m0, s13, 0xe000
	s_nop 0
	global_load_lds_dwordx4 v[196:197], off
	s_waitcnt vmcnt(8)
	s_waitcnt lgkmcnt(0)
	s_barrier
	s_setprio 1
	s_waitcnt lgkmcnt(0)
	v_mfma_f32_16x16x32_bf16 v[126:129], v[136:139], v[172:175], v[126:129]
	v_mfma_f32_16x16x32_bf16 v[94:97], v[144:147], v[172:175], v[94:97]
	v_mfma_f32_16x16x32_bf16 v[122:125], v[136:139], v[180:183], v[122:125]
	v_mfma_f32_16x16x32_bf16 v[90:93], v[144:147], v[180:183], v[90:93]
	v_mfma_f32_16x16x32_bf16 v[118:121], v[136:139], v[188:191], v[118:121]
	v_mfma_f32_16x16x32_bf16 v[86:89], v[144:147], v[188:191], v[86:89]
	v_mfma_f32_16x16x32_bf16 v[114:117], v[136:139], v[206:209], v[114:117]
	v_mfma_f32_16x16x32_bf16 v[82:85], v[144:147], v[206:209], v[82:85]
	v_mfma_f32_16x16x32_bf16 v[126:129], v[140:143], v[176:179], v[126:129]
	v_mfma_f32_16x16x32_bf16 v[94:97], v[148:151], v[176:179], v[94:97]
	v_mfma_f32_16x16x32_bf16 v[122:125], v[140:143], v[184:187], v[122:125]
	v_mfma_f32_16x16x32_bf16 v[90:93], v[148:151], v[184:187], v[90:93]
	v_mfma_f32_16x16x32_bf16 v[118:121], v[140:143], v[192:195], v[118:121]
	v_mfma_f32_16x16x32_bf16 v[86:89], v[148:151], v[192:195], v[86:89]
	v_mfma_f32_16x16x32_bf16 v[114:117], v[140:143], v[210:213], v[114:117]
	v_mfma_f32_16x16x32_bf16 v[82:85], v[148:151], v[210:213], v[82:85]
	s_setprio 0
	s_setprio 1
	v_mfma_f32_16x16x32_bf16 v[62:65], v[152:155], v[172:175], v[62:65]
	v_mfma_f32_16x16x32_bf16 v[30:33], v[164:167], v[172:175], v[30:33]
	v_mfma_f32_16x16x32_bf16 v[58:61], v[152:155], v[180:183], v[58:61]
	v_mfma_f32_16x16x32_bf16 v[26:29], v[164:167], v[180:183], v[26:29]
	v_mfma_f32_16x16x32_bf16 v[54:57], v[152:155], v[188:191], v[54:57]
	v_mfma_f32_16x16x32_bf16 v[22:25], v[164:167], v[188:191], v[22:25]
	v_mfma_f32_16x16x32_bf16 v[50:53], v[152:155], v[206:209], v[50:53]
	v_mfma_f32_16x16x32_bf16 v[18:21], v[164:167], v[206:209], v[18:21]
	v_mfma_f32_16x16x32_bf16 v[62:65], v[160:163], v[176:179], v[62:65]
	v_mfma_f32_16x16x32_bf16 v[30:33], v[168:171], v[176:179], v[30:33]
	v_mfma_f32_16x16x32_bf16 v[58:61], v[160:163], v[184:187], v[58:61]
	v_mfma_f32_16x16x32_bf16 v[26:29], v[168:171], v[184:187], v[26:29]
	v_mfma_f32_16x16x32_bf16 v[54:57], v[160:163], v[192:195], v[54:57]
	v_mfma_f32_16x16x32_bf16 v[22:25], v[168:171], v[192:195], v[22:25]
	v_mfma_f32_16x16x32_bf16 v[50:53], v[160:163], v[210:213], v[50:53]
	v_mfma_f32_16x16x32_bf16 v[18:21], v[168:171], v[210:213], v[18:21]
	s_setprio 0
	s_barrier
	s_add_i32 s36, s36, s63
	v_lshl_add_u64 v[196:197], s[4:5], 0, v[0:1]
	s_mov_b32 m0, s36
	ds_read_b128 v[172:175], v159 offset:16384
	ds_read_b128 v[176:179], v159 offset:17408
	ds_read_b128 v[180:183], v159 offset:18432
	ds_read_b128 v[184:187], v159 offset:19456
	ds_read_b128 v[188:191], v159 offset:20480
	ds_read_b128 v[192:195], v159 offset:21504
	ds_read_b128 v[206:209], v159 offset:22528
	ds_read_b128 v[210:213], v159 offset:23552
	global_load_lds_dwordx4 v[196:197], off
	s_add_i32 m0, s36, 0x2000
	s_add_u32 s40, s4, 0x40000
	v_lshl_add_u64 v[202:203], s[4:5], 0, v[130:131]
	s_addc_u32 s41, s5, 0
	s_add_i32 s36, s42, s63
	global_load_lds_dwordx4 v[202:203], off
	v_lshl_add_u64 v[214:215], s[40:41], 0, v[0:1]
	s_mov_b32 m0, s36
	v_lshl_add_u64 v[216:217], s[16:17], 0, v[130:131]
	global_load_lds_dwordx4 v[214:215], off
	v_lshl_add_u64 v[214:215], s[40:41], 0, v[130:131]
	s_add_i32 m0, s36, 0x2000
	s_mov_b64 s[44:45], 0x80
	global_load_lds_dwordx4 v[214:215], off
	v_lshl_add_u64 v[214:215], s[16:17], 0, v[0:1]
	s_mov_b32 m0, s13
	s_nop 0
	global_load_lds_dwordx4 v[214:215], off
	s_mov_b32 m0, s21
	s_nop 0
	global_load_lds_dwordx4 v[216:217], off
	s_waitcnt vmcnt(8)
	s_waitcnt lgkmcnt(0)
	s_barrier
	s_setprio 1
	s_waitcnt lgkmcnt(0)
	v_mfma_f32_16x16x32_bf16 v[110:113], v[136:139], v[172:175], v[110:113]
	v_mfma_f32_16x16x32_bf16 v[78:81], v[144:147], v[172:175], v[78:81]
	v_mfma_f32_16x16x32_bf16 v[106:109], v[136:139], v[180:183], v[106:109]
	v_mfma_f32_16x16x32_bf16 v[74:77], v[144:147], v[180:183], v[74:77]
	v_mfma_f32_16x16x32_bf16 v[102:105], v[136:139], v[188:191], v[102:105]
	v_mfma_f32_16x16x32_bf16 v[70:73], v[144:147], v[188:191], v[70:73]
	v_mfma_f32_16x16x32_bf16 v[98:101], v[136:139], v[206:209], v[98:101]
	v_mfma_f32_16x16x32_bf16 v[66:69], v[144:147], v[206:209], v[66:69]
	v_mfma_f32_16x16x32_bf16 v[110:113], v[140:143], v[176:179], v[110:113]
	v_mfma_f32_16x16x32_bf16 v[78:81], v[148:151], v[176:179], v[78:81]
	v_mfma_f32_16x16x32_bf16 v[106:109], v[140:143], v[184:187], v[106:109]
	v_mfma_f32_16x16x32_bf16 v[74:77], v[148:151], v[184:187], v[74:77]
	v_mfma_f32_16x16x32_bf16 v[102:105], v[140:143], v[192:195], v[102:105]
	v_mfma_f32_16x16x32_bf16 v[70:73], v[148:151], v[192:195], v[70:73]
	v_mfma_f32_16x16x32_bf16 v[98:101], v[140:143], v[210:213], v[98:101]
	v_mfma_f32_16x16x32_bf16 v[66:69], v[148:151], v[210:213], v[66:69]
	s_setprio 0
	s_setprio 1
	v_mfma_f32_16x16x32_bf16 v[46:49], v[152:155], v[172:175], v[46:49]
	v_mfma_f32_16x16x32_bf16 v[14:17], v[164:167], v[172:175], v[14:17]
	v_mfma_f32_16x16x32_bf16 v[42:45], v[152:155], v[180:183], v[42:45]
	v_mfma_f32_16x16x32_bf16 v[10:13], v[164:167], v[180:183], v[10:13]
	v_mfma_f32_16x16x32_bf16 v[38:41], v[152:155], v[188:191], v[38:41]
	v_mfma_f32_16x16x32_bf16 v[6:9], v[164:167], v[188:191], v[6:9]
	v_mfma_f32_16x16x32_bf16 v[34:37], v[152:155], v[206:209], v[34:37]
	v_mfma_f32_16x16x32_bf16 v[2:5], v[164:167], v[206:209], v[2:5]
	v_mfma_f32_16x16x32_bf16 v[46:49], v[160:163], v[176:179], v[46:49]
	v_mfma_f32_16x16x32_bf16 v[14:17], v[168:171], v[176:179], v[14:17]
	v_mfma_f32_16x16x32_bf16 v[42:45], v[160:163], v[184:187], v[42:45]
	v_mfma_f32_16x16x32_bf16 v[10:13], v[168:171], v[184:187], v[10:13]
	v_mfma_f32_16x16x32_bf16 v[38:41], v[160:163], v[192:195], v[38:41]
	v_mfma_f32_16x16x32_bf16 v[6:9], v[168:171], v[192:195], v[6:9]
	v_mfma_f32_16x16x32_bf16 v[34:37], v[160:163], v[210:213], v[34:37]
	v_mfma_f32_16x16x32_bf16 v[2:5], v[168:171], v[210:213], v[2:5]
	s_setprio 0
	s_barrier
	s_add_i32 s36, 0, 0x18000
	s_add_i32 s40, 0, 0x1c000
	v_add_u32_e32 v148, s36, v158
	v_add_u32_e32 v168, s40, v158
	ds_read_b128 v[136:139], v148
	ds_read_b128 v[140:143], v148 offset:1024
	ds_read_b128 v[144:147], v148 offset:2048
	ds_read_b128 v[148:151], v148 offset:3072
	ds_read_b128 v[152:155], v168
	ds_read_b128 v[160:163], v168 offset:1024
	ds_read_b128 v[164:167], v168 offset:2048
	ds_read_b128 v[168:171], v168 offset:3072
	s_add_u32 s16, s16, 0x40000
	s_addc_u32 s17, s17, 0
	s_mov_b32 m0, s22
	v_lshl_add_u64 v[218:219], s[16:17], 0, v[0:1]
	ds_read_b128 v[172:175], v159 offset:32768
	ds_read_b128 v[176:179], v159 offset:33792
	ds_read_b128 v[180:183], v159 offset:34816
	ds_read_b128 v[184:187], v159 offset:35840
	ds_read_b128 v[188:191], v159 offset:36864
	ds_read_b128 v[192:195], v159 offset:37888
	ds_read_b128 v[206:209], v159 offset:38912
	ds_read_b128 v[210:213], v159 offset:39936
	global_load_lds_dwordx4 v[218:219], off
	v_lshl_add_u64 v[218:219], s[16:17], 0, v[130:131]
	s_mov_b32 m0, s23
	s_nop 0
	global_load_lds_dwordx4 v[218:219], off
	s_waitcnt vmcnt(8)
	s_waitcnt lgkmcnt(0)
	s_barrier
	s_setprio 1
	s_waitcnt lgkmcnt(0)
	v_mfma_f32_16x16x32_bf16 v[126:129], v[136:139], v[172:175], v[126:129]
	v_mfma_f32_16x16x32_bf16 v[94:97], v[144:147], v[172:175], v[94:97]
	v_mfma_f32_16x16x32_bf16 v[122:125], v[136:139], v[180:183], v[122:125]
	v_mfma_f32_16x16x32_bf16 v[90:93], v[144:147], v[180:183], v[90:93]
	v_mfma_f32_16x16x32_bf16 v[118:121], v[136:139], v[188:191], v[118:121]
	v_mfma_f32_16x16x32_bf16 v[86:89], v[144:147], v[188:191], v[86:89]
	v_mfma_f32_16x16x32_bf16 v[114:117], v[136:139], v[206:209], v[114:117]
	v_mfma_f32_16x16x32_bf16 v[82:85], v[144:147], v[206:209], v[82:85]
	v_mfma_f32_16x16x32_bf16 v[126:129], v[140:143], v[176:179], v[126:129]
	v_mfma_f32_16x16x32_bf16 v[94:97], v[148:151], v[176:179], v[94:97]
	v_mfma_f32_16x16x32_bf16 v[122:125], v[140:143], v[184:187], v[122:125]
	v_mfma_f32_16x16x32_bf16 v[90:93], v[148:151], v[184:187], v[90:93]
	v_mfma_f32_16x16x32_bf16 v[118:121], v[140:143], v[192:195], v[118:121]
	v_mfma_f32_16x16x32_bf16 v[86:89], v[148:151], v[192:195], v[86:89]
	v_mfma_f32_16x16x32_bf16 v[114:117], v[140:143], v[210:213], v[114:117]
	v_mfma_f32_16x16x32_bf16 v[82:85], v[148:151], v[210:213], v[82:85]
	s_setprio 0
	s_setprio 1
	v_mfma_f32_16x16x32_bf16 v[62:65], v[152:155], v[172:175], v[62:65]
	v_mfma_f32_16x16x32_bf16 v[30:33], v[164:167], v[172:175], v[30:33]
	v_mfma_f32_16x16x32_bf16 v[58:61], v[152:155], v[180:183], v[58:61]
	v_mfma_f32_16x16x32_bf16 v[26:29], v[164:167], v[180:183], v[26:29]
	v_mfma_f32_16x16x32_bf16 v[54:57], v[152:155], v[188:191], v[54:57]
	v_mfma_f32_16x16x32_bf16 v[22:25], v[164:167], v[188:191], v[22:25]
	v_mfma_f32_16x16x32_bf16 v[50:53], v[152:155], v[206:209], v[50:53]
	v_mfma_f32_16x16x32_bf16 v[18:21], v[164:167], v[206:209], v[18:21]
	v_mfma_f32_16x16x32_bf16 v[62:65], v[160:163], v[176:179], v[62:65]
	v_mfma_f32_16x16x32_bf16 v[30:33], v[168:171], v[176:179], v[30:33]
	v_mfma_f32_16x16x32_bf16 v[58:61], v[160:163], v[184:187], v[58:61]
	v_mfma_f32_16x16x32_bf16 v[26:29], v[168:171], v[184:187], v[26:29]
	v_mfma_f32_16x16x32_bf16 v[54:57], v[160:163], v[192:195], v[54:57]
	v_mfma_f32_16x16x32_bf16 v[22:25], v[168:171], v[192:195], v[22:25]
	v_mfma_f32_16x16x32_bf16 v[50:53], v[160:163], v[210:213], v[50:53]
	v_mfma_f32_16x16x32_bf16 v[18:21], v[168:171], v[210:213], v[18:21]
	s_setprio 0
	s_barrier
	s_add_i32 s16, s36, s63
	v_lshl_add_u64 v[196:197], v[196:197], 0, s[44:45]
	s_mov_b32 m0, s16
	ds_read_b128 v[172:175], v159 offset:49152
	ds_read_b128 v[176:179], v159 offset:50176
	ds_read_b128 v[180:183], v159 offset:51200
	ds_read_b128 v[184:187], v159 offset:52224
	ds_read_b128 v[188:191], v159 offset:53248
	ds_read_b128 v[192:195], v159 offset:54272
	ds_read_b128 v[206:209], v159 offset:55296
	ds_read_b128 v[210:213], v159 offset:56320
	global_load_lds_dwordx4 v[196:197], off
	s_add_i32 m0, s16, 0x2000
	s_add_u32 s4, s4, 0x40080
	v_lshl_add_u64 v[196:197], v[202:203], 0, s[44:45]
	s_addc_u32 s5, s5, 0
	s_add_i32 s16, s40, s63
	global_load_lds_dwordx4 v[196:197], off
	v_lshl_add_u64 v[196:197], s[4:5], 0, v[0:1]
	s_mov_b32 m0, s16
	s_mov_b64 s[40:41], 0x80
	global_load_lds_dwordx4 v[196:197], off
	v_lshl_add_u64 v[196:197], s[4:5], 0, v[130:131]
	s_add_i32 m0, s16, 0x2000
	s_nop 0
	global_load_lds_dwordx4 v[196:197], off
	v_lshl_add_u64 v[196:197], v[214:215], 0, s[40:41]
	s_mov_b32 m0, s24
	s_nop 0
	global_load_lds_dwordx4 v[196:197], off
	v_lshl_add_u64 v[196:197], v[216:217], 0, s[40:41]
	s_mov_b32 m0, s25
	s_nop 0
	global_load_lds_dwordx4 v[196:197], off
	s_waitcnt vmcnt(8)
	s_waitcnt lgkmcnt(0)
	s_barrier
	s_setprio 1
	s_waitcnt lgkmcnt(0)
	v_mfma_f32_16x16x32_bf16 v[110:113], v[136:139], v[172:175], v[110:113]
	v_mfma_f32_16x16x32_bf16 v[78:81], v[144:147], v[172:175], v[78:81]
	v_mfma_f32_16x16x32_bf16 v[106:109], v[136:139], v[180:183], v[106:109]
	v_mfma_f32_16x16x32_bf16 v[74:77], v[144:147], v[180:183], v[74:77]
	v_mfma_f32_16x16x32_bf16 v[102:105], v[136:139], v[188:191], v[102:105]
	v_mfma_f32_16x16x32_bf16 v[70:73], v[144:147], v[188:191], v[70:73]
	v_mfma_f32_16x16x32_bf16 v[98:101], v[136:139], v[206:209], v[98:101]
	v_mfma_f32_16x16x32_bf16 v[66:69], v[144:147], v[206:209], v[66:69]
	v_mfma_f32_16x16x32_bf16 v[110:113], v[140:143], v[176:179], v[110:113]
	v_mfma_f32_16x16x32_bf16 v[78:81], v[148:151], v[176:179], v[78:81]
	v_mfma_f32_16x16x32_bf16 v[106:109], v[140:143], v[184:187], v[106:109]
	v_mfma_f32_16x16x32_bf16 v[74:77], v[148:151], v[184:187], v[74:77]
	v_mfma_f32_16x16x32_bf16 v[102:105], v[140:143], v[192:195], v[102:105]
	v_mfma_f32_16x16x32_bf16 v[70:73], v[148:151], v[192:195], v[70:73]
	v_mfma_f32_16x16x32_bf16 v[98:101], v[140:143], v[210:213], v[98:101]
	v_mfma_f32_16x16x32_bf16 v[66:69], v[148:151], v[210:213], v[66:69]
	s_setprio 0
	s_setprio 1
	v_mfma_f32_16x16x32_bf16 v[46:49], v[152:155], v[172:175], v[46:49]
	v_mfma_f32_16x16x32_bf16 v[14:17], v[164:167], v[172:175], v[14:17]
	v_mfma_f32_16x16x32_bf16 v[42:45], v[152:155], v[180:183], v[42:45]
	v_mfma_f32_16x16x32_bf16 v[10:13], v[164:167], v[180:183], v[10:13]
	v_mfma_f32_16x16x32_bf16 v[38:41], v[152:155], v[188:191], v[38:41]
	v_mfma_f32_16x16x32_bf16 v[6:9], v[164:167], v[188:191], v[6:9]
	v_mfma_f32_16x16x32_bf16 v[34:37], v[152:155], v[206:209], v[34:37]
	v_mfma_f32_16x16x32_bf16 v[2:5], v[164:167], v[206:209], v[2:5]
	v_mfma_f32_16x16x32_bf16 v[46:49], v[160:163], v[176:179], v[46:49]
	v_mfma_f32_16x16x32_bf16 v[14:17], v[168:171], v[176:179], v[14:17]
	v_mfma_f32_16x16x32_bf16 v[42:45], v[160:163], v[184:187], v[42:45]
	v_mfma_f32_16x16x32_bf16 v[10:13], v[168:171], v[184:187], v[10:13]
	v_mfma_f32_16x16x32_bf16 v[38:41], v[160:163], v[192:195], v[38:41]
	v_mfma_f32_16x16x32_bf16 v[6:9], v[168:171], v[192:195], v[6:9]
	v_mfma_f32_16x16x32_bf16 v[34:37], v[160:163], v[210:213], v[34:37]
	v_mfma_f32_16x16x32_bf16 v[2:5], v[168:171], v[210:213], v[2:5]
	s_setprio 0
	s_add_i32 s35, s35, 2
	s_add_u32 s14, s14, 0x100
	s_addc_u32 s15, s15, 0
	s_add_u32 s30, s30, 0x100
	s_addc_u32 s34, s34, 0
	s_add_u32 s4, s14, 0xfffc0080
	s_addc_u32 s5, s15, -1
	s_add_i32 s36, 0, 0x10000
	s_cmp_eq_u32 s35, 12
	s_cselect_b32 s17, s3, s5
	s_cselect_b32 s16, s28, s4
	s_cselect_b32 s5, s1, s34
	s_cselect_b32 s4, s29, s30
	s_add_i32 s42, 0, 0x14000
	s_cmp_gt_u32 s35, 13
	s_barrier
	s_cbranch_scc0 .LBB0_1713
	v_readlane_b32 s4, v253, 25
	v_readlane_b32 s5, v253, 26
	s_and_b64 vcc, exec, s[4:5]
	s_cbranch_vccz .LBB0_1716
	s_barrier
